# GEMM K-loops without the per-segment s_setprio 1/0 toggles (all waves stay at priority 0)
# speedup vs baseline: 1.0138x; 1.0018x over previous
; #define PG8_STAGE(bufoff, gbase, voff) do { _Pragma("unroll") for (int _i = 0; _i < 2; ++_i) \
;         __builtin_amdgcn_global_load_lds((const unsigned*)((const char*)(gbase) + (voff)[_i]), (LAS unsigned*)(lds + (bufoff) + ldsw + _i * 8192), 16, 0, 0); } while (0)
; #define PG8_LDA(dst, b, h) do { _Pragma("unroll") for (int m = 0; m < 4; ++m) _Pragma("unroll") for (int k = 0; k < 2; ++k) dst[m][k] = *(const LAS bf16x8*)(lds + PG8_SA(b, h) + aoff + m * 2048 + k * 1024); } while (0)
; #define PG8_LDB(dst, b, h) do { _Pragma("unroll") for (int n = 0; n < 2; ++n) _Pragma("unroll") for (int k = 0; k < 2; ++k) dst[n][k] = *(const LAS bf16x8*)(lds + PG8_SB(b, h) + boff + n * 2048 + k * 1024); } while (0)
; #define PG8_MMA(ai, bj, At, Bt) do { __builtin_amdgcn_s_setprio(1); _Pragma("unroll") for (int m = 0; m < 4; ++m) _Pragma("unroll") for (int n = 0; n < 2; ++n) _Pragma("unroll") for (int k = 0; k < 2; ++k) \
;         acc[ai][bj][m][n] = __builtin_amdgcn_mfma_f32_16x16x32_bf16(Bt[n][k], At[m][k], acc[ai][bj][m][n], 0, 0, 0); __builtin_amdgcn_s_setprio(0); } while (0)
; #define PG8_WAIT_V(n) asm volatile("s_waitcnt vmcnt(" #n ")" ::: "memory")
; #define PG8_WAIT_L(n) asm volatile("s_waitcnt lgkmcnt(" #n ")" ::: "memory")
; #define PG8_BAR __builtin_amdgcn_s_barrier()
; template <class Epi, class Sched>
; DI void gemm_phase(LAS unsigned char* lds, const Sched& S, const Epi& E) {
;     ...
;         for (int t = 0; t < nt; t += 2) {
;             const bool last = (t == nt - 2);
;             const char* a1 = cA + (size_t)(t + 1) * kstep;
;             const char* a2 = last ? nA : cA + (size_t)(t + 2) * kstep; const char* b2 = last ? nB : cB + (size_t)(t + 2) * kstep;
;             const char* a3 = a2 + kstep; const char* b3 = b2 + kstep;
;             if constexpr (Epi::HOOK) { if (cur.ks < 0 && (t == 16 || t == 32)) E.hook(acc, cur, t >> 4, wr, wc, fr, fq); }
;             PG8_LDB(B0, 0, 0); PG8_LDB(B1, 0, 1); PG8_SCHED; PG8_LDA(At, 0, 0); PG8_STAGE(PG8_SA(1, 1), a1 + hstepA, voffA);
;             PG8_WAIT_V(8); PG8_WAIT_L(0); PG8_BAR; PG8_MMA(0, 0, At, B0); PG8_MMA(0, 1, At, B1); PG8_BAR; PG8_SCHED;
;             PG8_LDA(At, 0, 1); PG8_STAGE(PG8_SB(0, 0), b2, voffB); PG8_STAGE(PG8_SB(0, 1), b2 + hstepB, voffB); PG8_STAGE(PG8_SA(0, 0), a2, voffA);
;             PG8_WAIT_V(8); PG8_WAIT_L(0); PG8_BAR; PG8_MMA(1, 0, At, B0); PG8_MMA(1, 1, At, B1); PG8_BAR; PG8_SCHED;
.LBB0_156:
	v_add_u32_e32 v216, 0x10000, v145
	s_add_i32 s82, s8, 2
	s_add_u32 s9, s4, 0xfff80080
	s_addc_u32 s40, s5, -1
	s_add_i32 s83, 0, 0x10000
	s_cmp_eq_u32 s79, s8
	s_cselect_b32 s41, s42, s40
	s_cselect_b32 s40, s43, s9
	s_cselect_b32 s9, s53, s81
	s_cselect_b32 s8, s57, s80
	s_add_i32 s85, 0, 0x14000
	ds_read_b128 v[52:55], v216
	ds_read_b128 v[156:159], v216 offset:1024
	ds_read_b128 v[160:163], v216 offset:2048
	ds_read_b128 v[168:171], v216 offset:3072
	ds_read_b128 v[172:175], v216 offset:16384
	ds_read_b128 v[176:179], v216 offset:17408
	ds_read_b128 v[180:183], v216 offset:18432
	ds_read_b128 v[184:187], v216 offset:19456
	s_add_i32 m0, s62, 0xc000
	ds_read_b128 v[188:191], v166
	ds_read_b128 v[192:195], v166 offset:1024
	ds_read_b128 v[204:207], v166 offset:2048
	ds_read_b128 v[208:211], v166 offset:3072
	ds_read_b128 v[212:215], v166 offset:4096
	ds_read_b128 v[230:233], v166 offset:5120
	ds_read_b128 v[234:237], v166 offset:6144
	global_load_lds_dwordx4 v154, s[4:5]
	s_add_i32 m0, s62, 0xe000
	ds_read_b128 v[238:241], v166 offset:7168
	global_load_lds_dwordx4 v152, s[4:5]
	s_waitcnt vmcnt(8) lgkmcnt(0)
	s_barrier
	v_mfma_f32_16x16x32_bf16 v[132:135], v[52:55], v[188:191], v[132:135]
	v_mfma_f32_16x16x32_bf16 v[128:131], v[160:163], v[188:191], v[128:131]
	v_mfma_f32_16x16x32_bf16 v[116:119], v[52:55], v[204:207], v[116:119]
	v_mfma_f32_16x16x32_bf16 v[112:115], v[160:163], v[204:207], v[112:115]
	v_mfma_f32_16x16x32_bf16 v[100:103], v[52:55], v[212:215], v[100:103]
	v_mfma_f32_16x16x32_bf16 v[96:99], v[160:163], v[212:215], v[96:99]
	v_mfma_f32_16x16x32_bf16 v[84:87], v[52:55], v[234:237], v[84:87]
	v_mfma_f32_16x16x32_bf16 v[80:83], v[160:163], v[234:237], v[80:83]
	v_mfma_f32_16x16x32_bf16 v[132:135], v[156:159], v[192:195], v[132:135]
	v_mfma_f32_16x16x32_bf16 v[128:131], v[168:171], v[192:195], v[128:131]
	v_mfma_f32_16x16x32_bf16 v[116:119], v[156:159], v[208:211], v[116:119]
	v_mfma_f32_16x16x32_bf16 v[112:115], v[168:171], v[208:211], v[112:115]
	v_mfma_f32_16x16x32_bf16 v[100:103], v[156:159], v[230:233], v[100:103]
	v_mfma_f32_16x16x32_bf16 v[96:99], v[168:171], v[230:233], v[96:99]
	v_mfma_f32_16x16x32_bf16 v[84:87], v[156:159], v[238:241], v[84:87]
	v_mfma_f32_16x16x32_bf16 v[80:83], v[168:171], v[238:241], v[80:83]
	v_mfma_f32_16x16x32_bf16 v[124:127], v[172:175], v[188:191], v[124:127]
	v_mfma_f32_16x16x32_bf16 v[120:123], v[180:183], v[188:191], v[120:123]
	v_mfma_f32_16x16x32_bf16 v[108:111], v[172:175], v[204:207], v[108:111]
	v_mfma_f32_16x16x32_bf16 v[104:107], v[180:183], v[204:207], v[104:107]
	v_mfma_f32_16x16x32_bf16 v[92:95], v[172:175], v[212:215], v[92:95]
	v_mfma_f32_16x16x32_bf16 v[88:91], v[180:183], v[212:215], v[88:91]
	v_mfma_f32_16x16x32_bf16 v[76:79], v[172:175], v[234:237], v[76:79]
	v_mfma_f32_16x16x32_bf16 v[72:75], v[180:183], v[234:237], v[72:75]
	v_mfma_f32_16x16x32_bf16 v[124:127], v[176:179], v[192:195], v[124:127]
	v_mfma_f32_16x16x32_bf16 v[120:123], v[184:187], v[192:195], v[120:123]
	v_mfma_f32_16x16x32_bf16 v[108:111], v[176:179], v[208:211], v[108:111]
	v_mfma_f32_16x16x32_bf16 v[104:107], v[184:187], v[208:211], v[104:107]
	v_mfma_f32_16x16x32_bf16 v[92:95], v[176:179], v[230:233], v[92:95]
	v_mfma_f32_16x16x32_bf16 v[88:91], v[184:187], v[230:233], v[88:91]
	v_mfma_f32_16x16x32_bf16 v[76:79], v[176:179], v[238:241], v[76:79]
	v_mfma_f32_16x16x32_bf16 v[72:75], v[184:187], v[238:241], v[72:75]
	s_barrier
	s_add_i32 s83, s83, s27
	s_mov_b32 m0, s83
	ds_read_b128 v[188:191], v166 offset:16384
	ds_read_b128 v[192:195], v166 offset:17408
	ds_read_b128 v[204:207], v166 offset:18432
	ds_read_b128 v[208:211], v166 offset:19456
	global_load_lds_dwordx4 v138, s[8:9]
	s_add_i32 m0, s83, 0x2000
	s_add_u32 s86, s8, 0x80000
	s_addc_u32 s87, s9, 0
	s_add_i32 s83, s85, s27
	global_load_lds_dwordx4 v142, s[8:9]
	s_mov_b32 m0, s83
	ds_read_b128 v[238:241], v166 offset:23552
	global_load_lds_dwordx4 v138, s[86:87]
	s_add_i32 m0, s83, 0x2000
	ds_read_b128 v[234:237], v166 offset:22528
	global_load_lds_dwordx4 v142, s[86:87]
	s_add_u32 s98, s40, 0x80
	s_addc_u32 s99, s41, 0
	s_mov_b32 m0, s62
	ds_read_b128 v[230:233], v166 offset:21504
	global_load_lds_dwordx4 v136, s[40:41]
	s_mov_b32 m0, s63
	ds_read_b128 v[212:215], v166 offset:20480
	global_load_lds_dwordx4 v140, s[40:41]
	s_waitcnt vmcnt(8) lgkmcnt(0)
	s_barrier
	v_mfma_f32_16x16x32_bf16 v[68:71], v[52:55], v[188:191], v[68:71]
	v_mfma_f32_16x16x32_bf16 v[64:67], v[160:163], v[188:191], v[64:67]
	v_mfma_f32_16x16x32_bf16 v[48:51], v[52:55], v[204:207], v[48:51]
	v_mfma_f32_16x16x32_bf16 v[44:47], v[160:163], v[204:207], v[44:47]
	v_mfma_f32_16x16x32_bf16 v[32:35], v[52:55], v[212:215], v[32:35]
	v_mfma_f32_16x16x32_bf16 v[28:31], v[160:163], v[212:215], v[28:31]
	v_mfma_f32_16x16x32_bf16 v[16:19], v[52:55], v[234:237], v[16:19]
	v_mfma_f32_16x16x32_bf16 v[12:15], v[160:163], v[234:237], v[12:15]
	v_mfma_f32_16x16x32_bf16 v[68:71], v[156:159], v[192:195], v[68:71]
	v_mfma_f32_16x16x32_bf16 v[64:67], v[168:171], v[192:195], v[64:67]
	v_mfma_f32_16x16x32_bf16 v[48:51], v[156:159], v[208:211], v[48:51]
	v_mfma_f32_16x16x32_bf16 v[44:47], v[168:171], v[208:211], v[44:47]
	v_mfma_f32_16x16x32_bf16 v[32:35], v[156:159], v[230:233], v[32:35]
	v_mfma_f32_16x16x32_bf16 v[28:31], v[168:171], v[230:233], v[28:31]
	v_mfma_f32_16x16x32_bf16 v[16:19], v[156:159], v[238:241], v[16:19]
	v_mfma_f32_16x16x32_bf16 v[12:15], v[168:171], v[238:241], v[12:15]
	v_mfma_f32_16x16x32_bf16 v[56:59], v[180:183], v[188:191], v[56:59]
	v_mfma_f32_16x16x32_bf16 v[40:43], v[172:175], v[204:207], v[40:43]
	v_mfma_f32_16x16x32_bf16 v[36:39], v[180:183], v[204:207], v[36:39]
	v_mfma_f32_16x16x32_bf16 v[24:27], v[172:175], v[212:215], v[24:27]
	v_mfma_f32_16x16x32_bf16 v[20:23], v[180:183], v[212:215], v[20:23]
	v_mfma_f32_16x16x32_bf16 v[8:11], v[172:175], v[234:237], v[8:11]
	v_mfma_f32_16x16x32_bf16 v[4:7], v[180:183], v[234:237], v[4:7]
	v_mfma_f32_16x16x32_bf16 v[52:55], v[172:175], v[188:191], v[60:63]
	v_mfma_f32_16x16x32_bf16 v[56:59], v[184:187], v[192:195], v[56:59]
	v_mfma_f32_16x16x32_bf16 v[40:43], v[176:179], v[208:211], v[40:43]
	v_mfma_f32_16x16x32_bf16 v[36:39], v[184:187], v[208:211], v[36:39]
	v_mfma_f32_16x16x32_bf16 v[24:27], v[176:179], v[230:233], v[24:27]
	v_mfma_f32_16x16x32_bf16 v[20:23], v[184:187], v[230:233], v[20:23]
	v_mfma_f32_16x16x32_bf16 v[8:11], v[176:179], v[238:241], v[8:11]
	v_mfma_f32_16x16x32_bf16 v[4:7], v[184:187], v[238:241], v[4:7]
	v_mfma_f32_16x16x32_bf16 v[52:55], v[176:179], v[192:195], v[52:55]
	s_barrier
; #define PG8_STAGE(bufoff, gbase, voff) do { _Pragma("unroll") for (int _i = 0; _i < 2; ++_i) \
;         __builtin_amdgcn_global_load_lds((const unsigned*)((const char*)(gbase) + (voff)[_i]), (LAS unsigned*)(lds + (bufoff) + ldsw + _i * 8192), 16, 0, 0); } while (0)
; #define PG8_LDA(dst, b, h) do { _Pragma("unroll") for (int m = 0; m < 4; ++m) _Pragma("unroll") for (int k = 0; k < 2; ++k) dst[m][k] = *(const LAS bf16x8*)(lds + PG8_SA(b, h) + aoff + m * 2048 + k * 1024); } while (0)
; #define PG8_LDB(dst, b, h) do { _Pragma("unroll") for (int n = 0; n < 2; ++n) _Pragma("unroll") for (int k = 0; k < 2; ++k) dst[n][k] = *(const LAS bf16x8*)(lds + PG8_SB(b, h) + boff + n * 2048 + k * 1024); } while (0)
; #define PG8_MMA(ai, bj, At, Bt) do { __builtin_amdgcn_s_setprio(1); _Pragma("unroll") for (int m = 0; m < 4; ++m) _Pragma("unroll") for (int n = 0; n < 2; ++n) _Pragma("unroll") for (int k = 0; k < 2; ++k) \
;         acc[ai][bj][m][n] = __builtin_amdgcn_mfma_f32_16x16x32_bf16(Bt[n][k], At[m][k], acc[ai][bj][m][n], 0, 0, 0); __builtin_amdgcn_s_setprio(0); } while (0)
; #define PG8_WAIT_V(n) asm volatile("s_waitcnt vmcnt(" #n ")" ::: "memory")
; #define PG8_WAIT_L(n) asm volatile("s_waitcnt lgkmcnt(" #n ")" ::: "memory")
; #define PG8_BAR __builtin_amdgcn_s_barrier()
; #define PG8_SCHED __builtin_amdgcn_sched_barrier(0)
; template <class Epi, class Sched>
; DI void gemm_phase(LAS unsigned char* lds, const Sched& S, const Epi& E) {
;     ...
;             PG8_LDB(B0, 1, 0); PG8_LDB(B1, 1, 1); PG8_SCHED; PG8_LDA(At, 1, 0); PG8_STAGE(PG8_SA(0, 1), a2 + hstepA, voffA);
;             PG8_WAIT_V(8); PG8_WAIT_L(0); PG8_BAR; PG8_MMA(0, 0, At, B0); PG8_MMA(0, 1, At, B1); PG8_BAR; PG8_SCHED;
;             PG8_LDA(At, 1, 1); PG8_STAGE(PG8_SB(1, 0), b3, voffB); PG8_STAGE(PG8_SB(1, 1), b3 + hstepB, voffB); PG8_STAGE(PG8_SA(1, 0), a3, voffA);
;             PG8_WAIT_V(8); PG8_WAIT_L(0); PG8_BAR; PG8_MMA(1, 0, At, B0); PG8_MMA(1, 1, At, B1); PG8_BAR; PG8_SCHED;
;         }
;         if (wr == 0) PG8_BAR;
	s_add_i32 s83, 0, 0x18000
	s_add_i32 s85, 0, 0x1c000
	ds_read_b128 v[60:63], v216 offset:32768
	ds_read_b128 v[156:159], v216 offset:33792
	ds_read_b128 v[160:163], v216 offset:34816
	ds_read_b128 v[168:171], v216 offset:35840
	ds_read_b128 v[172:175], v216 offset:49152
	ds_read_b128 v[176:179], v216 offset:50176
	ds_read_b128 v[180:183], v216 offset:51200
	ds_read_b128 v[184:187], v216 offset:52224
	s_add_u32 s40, s40, 0x80000
	s_addc_u32 s41, s41, 0
	s_mov_b32 m0, s64
	ds_read_b128 v[188:191], v166 offset:32768
	ds_read_b128 v[192:195], v166 offset:33792
	ds_read_b128 v[204:207], v166 offset:34816
	ds_read_b128 v[208:211], v166 offset:35840
	ds_read_b128 v[212:215], v166 offset:36864
	ds_read_b128 v[230:233], v166 offset:37888
	ds_read_b128 v[234:237], v166 offset:38912
	global_load_lds_dwordx4 v136, s[40:41]
	s_mov_b32 m0, s65
	ds_read_b128 v[238:241], v166 offset:39936
	global_load_lds_dwordx4 v140, s[40:41]
	s_waitcnt vmcnt(8) lgkmcnt(0)
	s_barrier
	v_mfma_f32_16x16x32_bf16 v[132:135], v[60:63], v[188:191], v[132:135]
	v_mfma_f32_16x16x32_bf16 v[128:131], v[160:163], v[188:191], v[128:131]
	v_mfma_f32_16x16x32_bf16 v[116:119], v[60:63], v[204:207], v[116:119]
	v_mfma_f32_16x16x32_bf16 v[112:115], v[160:163], v[204:207], v[112:115]
	v_mfma_f32_16x16x32_bf16 v[100:103], v[60:63], v[212:215], v[100:103]
	v_mfma_f32_16x16x32_bf16 v[96:99], v[160:163], v[212:215], v[96:99]
	v_mfma_f32_16x16x32_bf16 v[84:87], v[60:63], v[234:237], v[84:87]
	v_mfma_f32_16x16x32_bf16 v[80:83], v[160:163], v[234:237], v[80:83]
	v_mfma_f32_16x16x32_bf16 v[132:135], v[156:159], v[192:195], v[132:135]
	v_mfma_f32_16x16x32_bf16 v[128:131], v[168:171], v[192:195], v[128:131]
	v_mfma_f32_16x16x32_bf16 v[116:119], v[156:159], v[208:211], v[116:119]
	v_mfma_f32_16x16x32_bf16 v[112:115], v[168:171], v[208:211], v[112:115]
	v_mfma_f32_16x16x32_bf16 v[100:103], v[156:159], v[230:233], v[100:103]
	v_mfma_f32_16x16x32_bf16 v[96:99], v[168:171], v[230:233], v[96:99]
	v_mfma_f32_16x16x32_bf16 v[84:87], v[156:159], v[238:241], v[84:87]
	v_mfma_f32_16x16x32_bf16 v[80:83], v[168:171], v[238:241], v[80:83]
	v_mfma_f32_16x16x32_bf16 v[124:127], v[172:175], v[188:191], v[124:127]
	v_mfma_f32_16x16x32_bf16 v[120:123], v[180:183], v[188:191], v[120:123]
	v_mfma_f32_16x16x32_bf16 v[108:111], v[172:175], v[204:207], v[108:111]
	v_mfma_f32_16x16x32_bf16 v[104:107], v[180:183], v[204:207], v[104:107]
	v_mfma_f32_16x16x32_bf16 v[92:95], v[172:175], v[212:215], v[92:95]
	v_mfma_f32_16x16x32_bf16 v[88:91], v[180:183], v[212:215], v[88:91]
	v_mfma_f32_16x16x32_bf16 v[76:79], v[172:175], v[234:237], v[76:79]
	v_mfma_f32_16x16x32_bf16 v[72:75], v[180:183], v[234:237], v[72:75]
	v_mfma_f32_16x16x32_bf16 v[124:127], v[176:179], v[192:195], v[124:127]
	v_mfma_f32_16x16x32_bf16 v[120:123], v[184:187], v[192:195], v[120:123]
	v_mfma_f32_16x16x32_bf16 v[108:111], v[176:179], v[208:211], v[108:111]
	v_mfma_f32_16x16x32_bf16 v[104:107], v[184:187], v[208:211], v[104:107]
	v_mfma_f32_16x16x32_bf16 v[92:95], v[176:179], v[230:233], v[92:95]
	v_mfma_f32_16x16x32_bf16 v[88:91], v[184:187], v[230:233], v[88:91]
	v_mfma_f32_16x16x32_bf16 v[76:79], v[176:179], v[238:241], v[76:79]
	v_mfma_f32_16x16x32_bf16 v[72:75], v[184:187], v[238:241], v[72:75]
	s_barrier
	s_add_i32 s40, s83, s27
	s_add_u32 s8, s8, 0x80
	s_addc_u32 s9, s9, 0
	s_mov_b32 m0, s40
	ds_read_b128 v[188:191], v166 offset:49152
	ds_read_b128 v[192:195], v166 offset:50176
	ds_read_b128 v[204:207], v166 offset:51200
	ds_read_b128 v[208:211], v166 offset:52224
	global_load_lds_dwordx4 v138, s[8:9]
	s_add_i32 m0, s40, 0x2000
	s_add_i32 s40, s85, s27
	global_load_lds_dwordx4 v142, s[8:9]
	s_add_u32 s8, s8, 0x80000
	s_addc_u32 s9, s9, 0
	s_mov_b32 m0, s40
	ds_read_b128 v[238:241], v166 offset:56320
	global_load_lds_dwordx4 v138, s[8:9]
	s_add_i32 m0, s40, 0x2000
	ds_read_b128 v[234:237], v166 offset:55296
	global_load_lds_dwordx4 v142, s[8:9]
	s_mov_b32 m0, s72
	ds_read_b128 v[230:233], v166 offset:54272
	global_load_lds_dwordx4 v136, s[98:99]
	s_mov_b32 m0, s73
	ds_read_b128 v[212:215], v166 offset:53248
	global_load_lds_dwordx4 v140, s[98:99]
	s_waitcnt vmcnt(8) lgkmcnt(0)
	s_barrier
	v_mfma_f32_16x16x32_bf16 v[68:71], v[60:63], v[188:191], v[68:71]
	v_mfma_f32_16x16x32_bf16 v[64:67], v[160:163], v[188:191], v[64:67]
	v_mfma_f32_16x16x32_bf16 v[48:51], v[60:63], v[204:207], v[48:51]
	v_mfma_f32_16x16x32_bf16 v[44:47], v[160:163], v[204:207], v[44:47]
	v_mfma_f32_16x16x32_bf16 v[32:35], v[60:63], v[212:215], v[32:35]
	v_mfma_f32_16x16x32_bf16 v[28:31], v[160:163], v[212:215], v[28:31]
	v_mfma_f32_16x16x32_bf16 v[16:19], v[60:63], v[234:237], v[16:19]
	v_mfma_f32_16x16x32_bf16 v[12:15], v[160:163], v[234:237], v[12:15]
	v_mfma_f32_16x16x32_bf16 v[68:71], v[156:159], v[192:195], v[68:71]
	v_mfma_f32_16x16x32_bf16 v[64:67], v[168:171], v[192:195], v[64:67]
	v_mfma_f32_16x16x32_bf16 v[48:51], v[156:159], v[208:211], v[48:51]
	v_mfma_f32_16x16x32_bf16 v[44:47], v[168:171], v[208:211], v[44:47]
	v_mfma_f32_16x16x32_bf16 v[32:35], v[156:159], v[230:233], v[32:35]
	v_mfma_f32_16x16x32_bf16 v[28:31], v[168:171], v[230:233], v[28:31]
	v_mfma_f32_16x16x32_bf16 v[16:19], v[156:159], v[238:241], v[16:19]
	v_mfma_f32_16x16x32_bf16 v[12:15], v[168:171], v[238:241], v[12:15]
	v_mfma_f32_16x16x32_bf16 v[52:55], v[172:175], v[188:191], v[52:55]
	v_mfma_f32_16x16x32_bf16 v[60:63], v[176:179], v[192:195], v[52:55]
	v_mfma_f32_16x16x32_bf16 v[52:55], v[180:183], v[188:191], v[56:59]
	v_mfma_f32_16x16x32_bf16 v[40:43], v[172:175], v[204:207], v[40:43]
	v_mfma_f32_16x16x32_bf16 v[36:39], v[180:183], v[204:207], v[36:39]
	v_mfma_f32_16x16x32_bf16 v[24:27], v[172:175], v[212:215], v[24:27]
	v_mfma_f32_16x16x32_bf16 v[20:23], v[180:183], v[212:215], v[20:23]
	v_mfma_f32_16x16x32_bf16 v[8:11], v[172:175], v[234:237], v[8:11]
	v_mfma_f32_16x16x32_bf16 v[4:7], v[180:183], v[234:237], v[4:7]
	v_mfma_f32_16x16x32_bf16 v[56:59], v[184:187], v[192:195], v[52:55]
	v_mfma_f32_16x16x32_bf16 v[40:43], v[176:179], v[208:211], v[40:43]
	v_mfma_f32_16x16x32_bf16 v[36:39], v[184:187], v[208:211], v[36:39]
	v_mfma_f32_16x16x32_bf16 v[24:27], v[176:179], v[230:233], v[24:27]
	v_mfma_f32_16x16x32_bf16 v[20:23], v[184:187], v[230:233], v[20:23]
	v_mfma_f32_16x16x32_bf16 v[8:11], v[176:179], v[238:241], v[8:11]
	v_mfma_f32_16x16x32_bf16 v[4:7], v[184:187], v[238:241], v[4:7]
	s_barrier
	s_add_u32 s80, s80, 0x100
	s_addc_u32 s81, s81, 0
	s_add_u32 s4, s4, 0x100
	s_addc_u32 s5, s5, 0
	s_cmp_ge_i32 s82, s35
	s_mov_b32 s8, s82
	s_cbranch_scc0 .LBB0_156
	s_and_b64 vcc, exec, s[48:49]
	s_cbranch_vccz .LBB0_159
	s_barrier

; #define PG8_STAGE(bufoff, gbase, voff) do { _Pragma("unroll") for (int _i = 0; _i < 2; ++_i) \
;         __builtin_amdgcn_global_load_lds((const unsigned*)((const char*)(gbase) + (voff)[_i]), (LAS unsigned*)(lds + (bufoff) + ldsw + _i * 8192), 16, 0, 0); } while (0)
; #define PG8_LDA(dst, b, h) do { _Pragma("unroll") for (int m = 0; m < 4; ++m) _Pragma("unroll") for (int k = 0; k < 2; ++k) dst[m][k] = *(const LAS bf16x8*)(lds + PG8_SA(b, h) + aoff + m * 2048 + k * 1024); } while (0)
; #define PG8_LDB(dst, b, h) do { _Pragma("unroll") for (int n = 0; n < 2; ++n) _Pragma("unroll") for (int k = 0; k < 2; ++k) dst[n][k] = *(const LAS bf16x8*)(lds + PG8_SB(b, h) + boff + n * 2048 + k * 1024); } while (0)
; #define PG8_MMA(ai, bj, At, Bt) do { __builtin_amdgcn_s_setprio(1); _Pragma("unroll") for (int m = 0; m < 4; ++m) _Pragma("unroll") for (int n = 0; n < 2; ++n) _Pragma("unroll") for (int k = 0; k < 2; ++k) \
;         acc[ai][bj][m][n] = __builtin_amdgcn_mfma_f32_16x16x32_bf16(Bt[n][k], At[m][k], acc[ai][bj][m][n], 0, 0, 0); __builtin_amdgcn_s_setprio(0); } while (0)
; #define PG8_WAIT_V(n) asm volatile("s_waitcnt vmcnt(" #n ")" ::: "memory")
; #define PG8_WAIT_L(n) asm volatile("s_waitcnt lgkmcnt(" #n ")" ::: "memory")
; #define PG8_BAR __builtin_amdgcn_s_barrier()
; template <class Epi, class Sched>
; DI void gemm_phase(LAS unsigned char* lds, const Sched& S, const Epi& E) {
;     ...
;         for (int t = 0; t < nt; t += 2) {
;             const bool last = (t == nt - 2);
;             const char* a1 = cA + (size_t)(t + 1) * kstep;
;             const char* a2 = last ? nA : cA + (size_t)(t + 2) * kstep; const char* b2 = last ? nB : cB + (size_t)(t + 2) * kstep;
;             const char* a3 = a2 + kstep; const char* b3 = b2 + kstep;
;             if constexpr (Epi::HOOK) { if (cur.ks < 0 && (t == 16 || t == 32)) E.hook(acc, cur, t >> 4, wr, wc, fr, fq); }
;             PG8_LDB(B0, 0, 0); PG8_LDB(B1, 0, 1); PG8_SCHED; PG8_LDA(At, 0, 0); PG8_STAGE(PG8_SA(1, 1), a1 + hstepA, voffA);
;             PG8_WAIT_V(8); PG8_WAIT_L(0); PG8_BAR; PG8_MMA(0, 0, At, B0); PG8_MMA(0, 1, At, B1); PG8_BAR; PG8_SCHED;
;             PG8_LDA(At, 0, 1); PG8_STAGE(PG8_SB(0, 0), b2, voffB); PG8_STAGE(PG8_SB(0, 1), b2 + hstepB, voffB); PG8_STAGE(PG8_SA(0, 0), a2, voffA);
;             PG8_WAIT_V(8); PG8_WAIT_L(0); PG8_BAR; PG8_MMA(1, 0, At, B0); PG8_MMA(1, 1, At, B1); PG8_BAR; PG8_SCHED;
.LBB0_906:
	v_add_u32_e32 v158, 0x10000, v162
	s_add_i32 s23, s18, 2
	s_add_u32 s4, s40, 0x100
	s_addc_u32 s5, s41, 0
	s_cmp_eq_u32 s97, s18
	s_cselect_b32 s19, s79, s5
	s_cselect_b32 s18, s26, s4
	s_cselect_b32 s9, s27, s67
	s_cselect_b32 s8, s80, s66
	s_add_i32 s85, 0, 0x10000
	s_add_i32 vcc_lo, 0, 0x14000
	ds_read_b128 v[134:137], v158
	ds_read_b128 v[138:141], v158 offset:1024
	ds_read_b128 v[166:169], v158 offset:2048
	ds_read_b128 v[170:173], v158 offset:3072
	ds_read_b128 v[174:177], v158 offset:16384
	ds_read_b128 v[178:181], v158 offset:17408
	ds_read_b128 v[182:185], v158 offset:18432
	ds_read_b128 v[186:189], v158 offset:19456
	s_add_i32 m0, s39, 0xc000
	ds_read_b128 v[190:193], v164
	ds_read_b128 v[204:207], v164 offset:1024
	ds_read_b128 v[208:211], v164 offset:2048
	ds_read_b128 v[212:215], v164 offset:3072
	ds_read_b128 v[230:233], v164 offset:4096
	ds_read_b128 v[234:237], v164 offset:5120
	ds_read_b128 v[238:241], v164 offset:6144
	global_load_lds_dwordx4 v156, s[40:41]
	s_add_i32 m0, s39, 0xe000
	ds_read_b128 v[242:245], v164 offset:7168
	global_load_lds_dwordx4 v154, s[40:41]
	s_waitcnt vmcnt(8) lgkmcnt(0)
	s_barrier
	v_mfma_f32_16x16x32_bf16 v[130:133], v[134:137], v[190:193], v[130:133]
	v_mfma_f32_16x16x32_bf16 v[126:129], v[166:169], v[190:193], v[126:129]
	v_mfma_f32_16x16x32_bf16 v[114:117], v[134:137], v[208:211], v[114:117]
	v_mfma_f32_16x16x32_bf16 v[110:113], v[166:169], v[208:211], v[110:113]
	v_mfma_f32_16x16x32_bf16 v[98:101], v[134:137], v[230:233], v[98:101]
	v_mfma_f32_16x16x32_bf16 v[94:97], v[166:169], v[230:233], v[94:97]
	v_mfma_f32_16x16x32_bf16 v[82:85], v[134:137], v[238:241], v[82:85]
	v_mfma_f32_16x16x32_bf16 v[78:81], v[166:169], v[238:241], v[78:81]
	v_mfma_f32_16x16x32_bf16 v[130:133], v[138:141], v[204:207], v[130:133]
	v_mfma_f32_16x16x32_bf16 v[126:129], v[170:173], v[204:207], v[126:129]
	v_mfma_f32_16x16x32_bf16 v[114:117], v[138:141], v[212:215], v[114:117]
	v_mfma_f32_16x16x32_bf16 v[110:113], v[170:173], v[212:215], v[110:113]
	v_mfma_f32_16x16x32_bf16 v[98:101], v[138:141], v[234:237], v[98:101]
	v_mfma_f32_16x16x32_bf16 v[94:97], v[170:173], v[234:237], v[94:97]
	v_mfma_f32_16x16x32_bf16 v[82:85], v[138:141], v[242:245], v[82:85]
	v_mfma_f32_16x16x32_bf16 v[78:81], v[170:173], v[242:245], v[78:81]
	v_mfma_f32_16x16x32_bf16 v[122:125], v[174:177], v[190:193], v[122:125]
	v_mfma_f32_16x16x32_bf16 v[118:121], v[182:185], v[190:193], v[118:121]
	v_mfma_f32_16x16x32_bf16 v[106:109], v[174:177], v[208:211], v[106:109]
	v_mfma_f32_16x16x32_bf16 v[102:105], v[182:185], v[208:211], v[102:105]
	v_mfma_f32_16x16x32_bf16 v[90:93], v[174:177], v[230:233], v[90:93]
	v_mfma_f32_16x16x32_bf16 v[86:89], v[182:185], v[230:233], v[86:89]
	v_mfma_f32_16x16x32_bf16 v[74:77], v[174:177], v[238:241], v[74:77]
	v_mfma_f32_16x16x32_bf16 v[70:73], v[182:185], v[238:241], v[70:73]
	v_mfma_f32_16x16x32_bf16 v[122:125], v[178:181], v[204:207], v[122:125]
	v_mfma_f32_16x16x32_bf16 v[118:121], v[186:189], v[204:207], v[118:121]
	v_mfma_f32_16x16x32_bf16 v[106:109], v[178:181], v[212:215], v[106:109]
	v_mfma_f32_16x16x32_bf16 v[102:105], v[186:189], v[212:215], v[102:105]
	v_mfma_f32_16x16x32_bf16 v[90:93], v[178:181], v[234:237], v[90:93]
	v_mfma_f32_16x16x32_bf16 v[86:89], v[186:189], v[234:237], v[86:89]
	v_mfma_f32_16x16x32_bf16 v[74:77], v[178:181], v[242:245], v[74:77]
	v_mfma_f32_16x16x32_bf16 v[70:73], v[186:189], v[242:245], v[70:73]
	s_barrier
	s_add_i32 s40, s85, s38
	s_mov_b32 m0, s40
	ds_read_b128 v[190:193], v164 offset:16384
	ds_read_b128 v[204:207], v164 offset:17408
	ds_read_b128 v[208:211], v164 offset:18432
	ds_read_b128 v[212:215], v164 offset:19456
	global_load_lds_dwordx4 v144, s[8:9]
	s_add_i32 m0, s40, 0x2000
	s_add_u32 s40, s8, 0xc0000
	s_addc_u32 s41, s9, 0
	s_add_i32 s85, vcc_lo, s38
	global_load_lds_dwordx4 v148, s[8:9]
	s_mov_b32 m0, s85
	ds_read_b128 v[242:245], v164 offset:23552
	global_load_lds_dwordx4 v144, s[40:41]
	s_add_i32 m0, s85, 0x2000
	ds_read_b128 v[238:241], v164 offset:22528
	global_load_lds_dwordx4 v148, s[40:41]
	s_add_u32 s98, s18, 0x80
	s_addc_u32 s99, s19, 0
	s_mov_b32 m0, s39
	ds_read_b128 v[234:237], v164 offset:21504
	global_load_lds_dwordx4 v142, s[18:19]
	s_mov_b32 m0, s63
	ds_read_b128 v[230:233], v164 offset:20480
	global_load_lds_dwordx4 v146, s[18:19]
	s_waitcnt vmcnt(8) lgkmcnt(0)
	s_barrier
	v_mfma_f32_16x16x32_bf16 v[66:69], v[134:137], v[190:193], v[66:69]
	v_mfma_f32_16x16x32_bf16 v[62:65], v[166:169], v[190:193], v[62:65]
	v_mfma_f32_16x16x32_bf16 v[50:53], v[134:137], v[208:211], v[50:53]
	v_mfma_f32_16x16x32_bf16 v[46:49], v[166:169], v[208:211], v[46:49]
	v_mfma_f32_16x16x32_bf16 v[34:37], v[134:137], v[230:233], v[34:37]
	v_mfma_f32_16x16x32_bf16 v[30:33], v[166:169], v[230:233], v[30:33]
	v_mfma_f32_16x16x32_bf16 v[18:21], v[134:137], v[238:241], v[18:21]
	v_mfma_f32_16x16x32_bf16 v[14:17], v[166:169], v[238:241], v[14:17]
	v_mfma_f32_16x16x32_bf16 v[66:69], v[138:141], v[204:207], v[66:69]
	v_mfma_f32_16x16x32_bf16 v[62:65], v[170:173], v[204:207], v[62:65]
	v_mfma_f32_16x16x32_bf16 v[50:53], v[138:141], v[212:215], v[50:53]
	v_mfma_f32_16x16x32_bf16 v[46:49], v[170:173], v[212:215], v[46:49]
	v_mfma_f32_16x16x32_bf16 v[34:37], v[138:141], v[234:237], v[34:37]
	v_mfma_f32_16x16x32_bf16 v[30:33], v[170:173], v[234:237], v[30:33]
	v_mfma_f32_16x16x32_bf16 v[18:21], v[138:141], v[242:245], v[18:21]
	v_mfma_f32_16x16x32_bf16 v[14:17], v[170:173], v[242:245], v[14:17]
	v_mfma_f32_16x16x32_bf16 v[58:61], v[174:177], v[190:193], v[58:61]
	v_mfma_f32_16x16x32_bf16 v[54:57], v[182:185], v[190:193], v[54:57]
	v_mfma_f32_16x16x32_bf16 v[42:45], v[174:177], v[208:211], v[42:45]
	v_mfma_f32_16x16x32_bf16 v[38:41], v[182:185], v[208:211], v[38:41]
	v_mfma_f32_16x16x32_bf16 v[26:29], v[174:177], v[230:233], v[26:29]
	v_mfma_f32_16x16x32_bf16 v[22:25], v[182:185], v[230:233], v[22:25]
	v_mfma_f32_16x16x32_bf16 v[10:13], v[174:177], v[238:241], v[10:13]
	v_mfma_f32_16x16x32_bf16 v[4:7], v[182:185], v[238:241], v[6:9]
	v_mfma_f32_16x16x32_bf16 v[58:61], v[178:181], v[204:207], v[58:61]
	v_mfma_f32_16x16x32_bf16 v[54:57], v[186:189], v[204:207], v[54:57]
	v_mfma_f32_16x16x32_bf16 v[42:45], v[178:181], v[212:215], v[42:45]
	v_mfma_f32_16x16x32_bf16 v[38:41], v[186:189], v[212:215], v[38:41]
	v_mfma_f32_16x16x32_bf16 v[26:29], v[178:181], v[234:237], v[26:29]
	v_mfma_f32_16x16x32_bf16 v[22:25], v[186:189], v[234:237], v[22:25]
	v_mfma_f32_16x16x32_bf16 v[10:13], v[178:181], v[242:245], v[10:13]
	v_mfma_f32_16x16x32_bf16 v[4:7], v[186:189], v[242:245], v[4:7]
	s_barrier
; #define PG8_STAGE(bufoff, gbase, voff) do { _Pragma("unroll") for (int _i = 0; _i < 2; ++_i) \
;         __builtin_amdgcn_global_load_lds((const unsigned*)((const char*)(gbase) + (voff)[_i]), (LAS unsigned*)(lds + (bufoff) + ldsw + _i * 8192), 16, 0, 0); } while (0)
; #define PG8_LDA(dst, b, h) do { _Pragma("unroll") for (int m = 0; m < 4; ++m) _Pragma("unroll") for (int k = 0; k < 2; ++k) dst[m][k] = *(const LAS bf16x8*)(lds + PG8_SA(b, h) + aoff + m * 2048 + k * 1024); } while (0)
; #define PG8_LDB(dst, b, h) do { _Pragma("unroll") for (int n = 0; n < 2; ++n) _Pragma("unroll") for (int k = 0; k < 2; ++k) dst[n][k] = *(const LAS bf16x8*)(lds + PG8_SB(b, h) + boff + n * 2048 + k * 1024); } while (0)
; #define PG8_MMA(ai, bj, At, Bt) do { __builtin_amdgcn_s_setprio(1); _Pragma("unroll") for (int m = 0; m < 4; ++m) _Pragma("unroll") for (int n = 0; n < 2; ++n) _Pragma("unroll") for (int k = 0; k < 2; ++k) \
;         acc[ai][bj][m][n] = __builtin_amdgcn_mfma_f32_16x16x32_bf16(Bt[n][k], At[m][k], acc[ai][bj][m][n], 0, 0, 0); __builtin_amdgcn_s_setprio(0); } while (0)
; template <class Epi, class Sched>
; DI void gemm_phase(LAS unsigned char* lds, const Sched& S, const Epi& E) {
;     ...
;             if constexpr (Epi::HOOK) { if (cur.ks < 0 && (t == 16 || t == 32)) E.hook(acc, cur, t >> 4, wr, wc, fr, fq); }
;             PG8_LDB(B0, 0, 0); PG8_LDB(B1, 0, 1); PG8_SCHED; PG8_LDA(At, 0, 0); PG8_STAGE(PG8_SA(1, 1), a1 + hstepA, voffA);
;             PG8_WAIT_V(8); PG8_WAIT_L(0); PG8_BAR; PG8_MMA(0, 0, At, B0); PG8_MMA(0, 1, At, B1); PG8_BAR; PG8_SCHED;
;             PG8_LDA(At, 0, 1); PG8_STAGE(PG8_SB(0, 0), b2, voffB); PG8_STAGE(PG8_SB(0, 1), b2 + hstepB, voffB); PG8_STAGE(PG8_SA(0, 0), a2, voffA);
;             PG8_WAIT_V(8); PG8_WAIT_L(0); PG8_BAR; PG8_MMA(1, 0, At, B0); PG8_MMA(1, 1, At, B1); PG8_BAR; PG8_SCHED;
;             PG8_LDB(B0, 1, 0); PG8_LDB(B1, 1, 1); PG8_SCHED; PG8_LDA(At, 1, 0); PG8_STAGE(PG8_SA(0, 1), a2 + hstepA, voffA);
;             PG8_WAIT_V(8); PG8_WAIT_L(0); PG8_BAR; PG8_MMA(0, 0, At, B0); PG8_MMA(0, 1, At, B1); PG8_BAR; PG8_SCHED;
;             PG8_LDA(At, 1, 1); PG8_STAGE(PG8_SB(1, 0), b3, voffB); PG8_STAGE(PG8_SB(1, 1), b3 + hstepB, voffB); PG8_STAGE(PG8_SA(1, 0), a3, voffA);
;             PG8_WAIT_V(8); PG8_WAIT_L(0); PG8_BAR; PG8_MMA(1, 0, At, B0); PG8_MMA(1, 1, At, B1); PG8_BAR; PG8_SCHED;
;         }
;         if (wr == 0) PG8_BAR;
	s_add_i32 s40, 0, 0x18000
	s_add_i32 s41, 0, 0x1c000
	ds_read_b128 v[134:137], v158 offset:32768
	ds_read_b128 v[138:141], v158 offset:33792
	ds_read_b128 v[166:169], v158 offset:34816
	ds_read_b128 v[170:173], v158 offset:35840
	ds_read_b128 v[174:177], v158 offset:49152
	ds_read_b128 v[178:181], v158 offset:50176
	ds_read_b128 v[182:185], v158 offset:51200
	ds_read_b128 v[186:189], v158 offset:52224
	s_add_u32 s18, s18, 0xc0000
	s_addc_u32 s19, s19, 0
	s_mov_b32 m0, s64
	ds_read_b128 v[190:193], v164 offset:32768
	ds_read_b128 v[204:207], v164 offset:33792
	ds_read_b128 v[208:211], v164 offset:34816
	ds_read_b128 v[212:215], v164 offset:35840
	ds_read_b128 v[230:233], v164 offset:36864
	ds_read_b128 v[234:237], v164 offset:37888
	ds_read_b128 v[238:241], v164 offset:38912
	global_load_lds_dwordx4 v142, s[18:19]
	s_mov_b32 m0, s65
	ds_read_b128 v[242:245], v164 offset:39936
	global_load_lds_dwordx4 v146, s[18:19]
	s_waitcnt vmcnt(8) lgkmcnt(0)
	s_barrier
	v_mfma_f32_16x16x32_bf16 v[130:133], v[134:137], v[190:193], v[130:133]
	v_mfma_f32_16x16x32_bf16 v[126:129], v[166:169], v[190:193], v[126:129]
	v_mfma_f32_16x16x32_bf16 v[114:117], v[134:137], v[208:211], v[114:117]
	v_mfma_f32_16x16x32_bf16 v[110:113], v[166:169], v[208:211], v[110:113]
	v_mfma_f32_16x16x32_bf16 v[98:101], v[134:137], v[230:233], v[98:101]
	v_mfma_f32_16x16x32_bf16 v[94:97], v[166:169], v[230:233], v[94:97]
	v_mfma_f32_16x16x32_bf16 v[82:85], v[134:137], v[238:241], v[82:85]
	v_mfma_f32_16x16x32_bf16 v[78:81], v[166:169], v[238:241], v[78:81]
	v_mfma_f32_16x16x32_bf16 v[130:133], v[138:141], v[204:207], v[130:133]
	v_mfma_f32_16x16x32_bf16 v[126:129], v[170:173], v[204:207], v[126:129]
	v_mfma_f32_16x16x32_bf16 v[114:117], v[138:141], v[212:215], v[114:117]
	v_mfma_f32_16x16x32_bf16 v[110:113], v[170:173], v[212:215], v[110:113]
	v_mfma_f32_16x16x32_bf16 v[98:101], v[138:141], v[234:237], v[98:101]
	v_mfma_f32_16x16x32_bf16 v[94:97], v[170:173], v[234:237], v[94:97]
	v_mfma_f32_16x16x32_bf16 v[82:85], v[138:141], v[242:245], v[82:85]
	v_mfma_f32_16x16x32_bf16 v[78:81], v[170:173], v[242:245], v[78:81]
	v_mfma_f32_16x16x32_bf16 v[122:125], v[174:177], v[190:193], v[122:125]
	v_mfma_f32_16x16x32_bf16 v[118:121], v[182:185], v[190:193], v[118:121]
	v_mfma_f32_16x16x32_bf16 v[106:109], v[174:177], v[208:211], v[106:109]
	v_mfma_f32_16x16x32_bf16 v[102:105], v[182:185], v[208:211], v[102:105]
	v_mfma_f32_16x16x32_bf16 v[90:93], v[174:177], v[230:233], v[90:93]
	v_mfma_f32_16x16x32_bf16 v[86:89], v[182:185], v[230:233], v[86:89]
	v_mfma_f32_16x16x32_bf16 v[74:77], v[174:177], v[238:241], v[74:77]
	v_mfma_f32_16x16x32_bf16 v[70:73], v[182:185], v[238:241], v[70:73]
	v_mfma_f32_16x16x32_bf16 v[122:125], v[178:181], v[204:207], v[122:125]
	v_mfma_f32_16x16x32_bf16 v[118:121], v[186:189], v[204:207], v[118:121]
	v_mfma_f32_16x16x32_bf16 v[106:109], v[178:181], v[212:215], v[106:109]
	v_mfma_f32_16x16x32_bf16 v[102:105], v[186:189], v[212:215], v[102:105]
	v_mfma_f32_16x16x32_bf16 v[90:93], v[178:181], v[234:237], v[90:93]
	v_mfma_f32_16x16x32_bf16 v[86:89], v[186:189], v[234:237], v[86:89]
	v_mfma_f32_16x16x32_bf16 v[74:77], v[178:181], v[242:245], v[74:77]
	v_mfma_f32_16x16x32_bf16 v[70:73], v[186:189], v[242:245], v[70:73]
	s_barrier
	s_add_i32 s18, s40, s38
	s_add_u32 s8, s8, 0x80
	s_addc_u32 s9, s9, 0
	s_mov_b32 m0, s18
	ds_read_b128 v[190:193], v164 offset:49152
	ds_read_b128 v[204:207], v164 offset:50176
	ds_read_b128 v[208:211], v164 offset:51200
	ds_read_b128 v[212:215], v164 offset:52224
	global_load_lds_dwordx4 v144, s[8:9]
	s_add_i32 m0, s18, 0x2000
	s_add_i32 s18, s41, s38
	global_load_lds_dwordx4 v148, s[8:9]
	s_add_u32 s8, s8, 0xc0000
	s_addc_u32 s9, s9, 0
	s_mov_b32 m0, s18
	ds_read_b128 v[242:245], v164 offset:56320
	global_load_lds_dwordx4 v144, s[8:9]
	s_add_i32 m0, s18, 0x2000
	ds_read_b128 v[238:241], v164 offset:55296
	global_load_lds_dwordx4 v148, s[8:9]
	s_mov_b32 m0, s75
	ds_read_b128 v[234:237], v164 offset:54272
	global_load_lds_dwordx4 v142, s[98:99]
	s_mov_b32 m0, s81
	ds_read_b128 v[230:233], v164 offset:53248
	global_load_lds_dwordx4 v146, s[98:99]
	s_waitcnt vmcnt(8) lgkmcnt(0)
	s_barrier
	v_mfma_f32_16x16x32_bf16 v[66:69], v[134:137], v[190:193], v[66:69]
	v_mfma_f32_16x16x32_bf16 v[62:65], v[166:169], v[190:193], v[62:65]
	v_mfma_f32_16x16x32_bf16 v[50:53], v[134:137], v[208:211], v[50:53]
	v_mfma_f32_16x16x32_bf16 v[46:49], v[166:169], v[208:211], v[46:49]
	v_mfma_f32_16x16x32_bf16 v[34:37], v[134:137], v[230:233], v[34:37]
	v_mfma_f32_16x16x32_bf16 v[30:33], v[166:169], v[230:233], v[30:33]
	v_mfma_f32_16x16x32_bf16 v[18:21], v[134:137], v[238:241], v[18:21]
	v_mfma_f32_16x16x32_bf16 v[14:17], v[166:169], v[238:241], v[14:17]
	v_mfma_f32_16x16x32_bf16 v[66:69], v[138:141], v[204:207], v[66:69]
	v_mfma_f32_16x16x32_bf16 v[62:65], v[170:173], v[204:207], v[62:65]
	v_mfma_f32_16x16x32_bf16 v[50:53], v[138:141], v[212:215], v[50:53]
	v_mfma_f32_16x16x32_bf16 v[46:49], v[170:173], v[212:215], v[46:49]
	v_mfma_f32_16x16x32_bf16 v[34:37], v[138:141], v[234:237], v[34:37]
	v_mfma_f32_16x16x32_bf16 v[30:33], v[170:173], v[234:237], v[30:33]
	v_mfma_f32_16x16x32_bf16 v[18:21], v[138:141], v[242:245], v[18:21]
	v_mfma_f32_16x16x32_bf16 v[14:17], v[170:173], v[242:245], v[14:17]
	v_mfma_f32_16x16x32_bf16 v[58:61], v[174:177], v[190:193], v[58:61]
	v_mfma_f32_16x16x32_bf16 v[54:57], v[182:185], v[190:193], v[54:57]
	v_mfma_f32_16x16x32_bf16 v[42:45], v[174:177], v[208:211], v[42:45]
	v_mfma_f32_16x16x32_bf16 v[38:41], v[182:185], v[208:211], v[38:41]
	v_mfma_f32_16x16x32_bf16 v[26:29], v[174:177], v[230:233], v[26:29]
	v_mfma_f32_16x16x32_bf16 v[22:25], v[182:185], v[230:233], v[22:25]
	v_mfma_f32_16x16x32_bf16 v[8:11], v[174:177], v[238:241], v[10:13]
	v_mfma_f32_16x16x32_bf16 v[4:7], v[182:185], v[238:241], v[4:7]
	v_mfma_f32_16x16x32_bf16 v[58:61], v[178:181], v[204:207], v[58:61]
	v_mfma_f32_16x16x32_bf16 v[54:57], v[186:189], v[204:207], v[54:57]
	v_mfma_f32_16x16x32_bf16 v[42:45], v[178:181], v[212:215], v[42:45]
	v_mfma_f32_16x16x32_bf16 v[38:41], v[186:189], v[212:215], v[38:41]
	v_mfma_f32_16x16x32_bf16 v[26:29], v[178:181], v[234:237], v[26:29]
	v_mfma_f32_16x16x32_bf16 v[22:25], v[186:189], v[234:237], v[22:25]
	v_mfma_f32_16x16x32_bf16 v[10:13], v[178:181], v[242:245], v[8:11]
	v_mfma_f32_16x16x32_bf16 v[6:9], v[186:189], v[242:245], v[4:7]
	s_barrier
	s_add_i32 s22, s22, 1
	s_add_u32 s66, s66, 0x100
	s_addc_u32 s67, s67, 0
	s_cmp_ge_i32 s23, s10
	s_cbranch_scc1 .LBB0_908
	s_mov_b64 s[40:41], s[4:5]
	s_mov_b32 s18, s23
	s_andn2_b64 vcc, exec, s[56:57]
	s_cbranch_vccnz .LBB0_906
	s_branch .LBB0_900

; #define PG8_STAGE(bufoff, gbase, voff) do { _Pragma("unroll") for (int _i = 0; _i < 2; ++_i) \
;         __builtin_amdgcn_global_load_lds((const unsigned*)((const char*)(gbase) + (voff)[_i]), (LAS unsigned*)(lds + (bufoff) + ldsw + _i * 8192), 16, 0, 0); } while (0)
; #define PG8_LDA(dst, b, h) do { _Pragma("unroll") for (int m = 0; m < 4; ++m) _Pragma("unroll") for (int k = 0; k < 2; ++k) dst[m][k] = *(const LAS bf16x8*)(lds + PG8_SA(b, h) + aoff + m * 2048 + k * 1024); } while (0)
; #define PG8_LDB(dst, b, h) do { _Pragma("unroll") for (int n = 0; n < 2; ++n) _Pragma("unroll") for (int k = 0; k < 2; ++k) dst[n][k] = *(const LAS bf16x8*)(lds + PG8_SB(b, h) + boff + n * 2048 + k * 1024); } while (0)
; #define PG8_MMA(ai, bj, At, Bt) do { __builtin_amdgcn_s_setprio(1); _Pragma("unroll") for (int m = 0; m < 4; ++m) _Pragma("unroll") for (int n = 0; n < 2; ++n) _Pragma("unroll") for (int k = 0; k < 2; ++k) \
;         acc[ai][bj][m][n] = __builtin_amdgcn_mfma_f32_16x16x32_bf16(Bt[n][k], At[m][k], acc[ai][bj][m][n], 0, 0, 0); __builtin_amdgcn_s_setprio(0); } while (0)
; #define PG8_WAIT_V(n) asm volatile("s_waitcnt vmcnt(" #n ")" ::: "memory")
; #define PG8_WAIT_L(n) asm volatile("s_waitcnt lgkmcnt(" #n ")" ::: "memory")
; #define PG8_BAR __builtin_amdgcn_s_barrier()
; template <class Epi, class Sched>
; DI void gemm_phase(LAS unsigned char* lds, const Sched& S, const Epi& E) {
;     ...
;         for (int t = 0; t < nt; t += 2) {
;             const bool last = (t == nt - 2);
;             const char* a1 = cA + (size_t)(t + 1) * kstep;
;             const char* a2 = last ? nA : cA + (size_t)(t + 2) * kstep; const char* b2 = last ? nB : cB + (size_t)(t + 2) * kstep;
;             const char* a3 = a2 + kstep; const char* b3 = b2 + kstep;
;             if constexpr (Epi::HOOK) { if (cur.ks < 0 && (t == 16 || t == 32)) E.hook(acc, cur, t >> 4, wr, wc, fr, fq); }
;             PG8_LDB(B0, 0, 0); PG8_LDB(B1, 0, 1); PG8_SCHED; PG8_LDA(At, 0, 0); PG8_STAGE(PG8_SA(1, 1), a1 + hstepA, voffA);
;             PG8_WAIT_V(8); PG8_WAIT_L(0); PG8_BAR; PG8_MMA(0, 0, At, B0); PG8_MMA(0, 1, At, B1); PG8_BAR; PG8_SCHED;
;             PG8_LDA(At, 0, 1); PG8_STAGE(PG8_SB(0, 0), b2, voffB); PG8_STAGE(PG8_SB(0, 1), b2 + hstepB, voffB); PG8_STAGE(PG8_SA(0, 0), a2, voffA);
;             PG8_WAIT_V(8); PG8_WAIT_L(0); PG8_BAR; PG8_MMA(1, 0, At, B0); PG8_MMA(1, 1, At, B1); PG8_BAR; PG8_SCHED;
.LBB0_1104:
	v_add_u32_e32 v214, 0x10000, v197
	s_add_i32 s82, s52, 2
	s_add_u32 s53, s42, 0xfff80080
	s_addc_u32 s54, s43, -1
	s_add_i32 s83, 0, 0x10000
	s_cmp_eq_u32 s79, s52
	s_cselect_b32 s55, s56, s54
	s_cselect_b32 s54, s57, s53
	s_cselect_b32 s53, s58, s81
	s_cselect_b32 s52, s59, s80
	s_add_i32 s85, 0, 0x14000
	s_waitcnt vmcnt(0)
	ds_read_b128 v[84:87], v214
	ds_read_b128 v[88:91], v214 offset:1024
	ds_read_b128 v[104:107], v214 offset:2048
	ds_read_b128 v[112:115], v214 offset:3072
	ds_read_b128 v[124:127], v214 offset:16384
	ds_read_b128 v[136:139], v214 offset:17408
	ds_read_b128 v[148:151], v214 offset:18432
	ds_read_b128 v[160:163], v214 offset:19456
	s_add_i32 m0, s26, 0xc000
	ds_read_b128 v[164:167], v231
	ds_read_b128 v[168:171], v231 offset:1024
	ds_read_b128 v[172:175], v231 offset:2048
	ds_read_b128 v[176:179], v231 offset:3072
	ds_read_b128 v[180:183], v231 offset:4096
	ds_read_b128 v[184:187], v231 offset:5120
	ds_read_b128 v[188:191], v231 offset:6144
	global_load_lds_dwordx4 v212, s[42:43]
	s_add_i32 m0, s26, 0xe000
	ds_read_b128 v[192:195], v231 offset:7168
	global_load_lds_dwordx4 v210, s[42:43]
	s_waitcnt vmcnt(8) lgkmcnt(0)
	s_barrier
	v_mfma_f32_16x16x32_bf16 v[156:159], v[84:87], v[164:167], v[156:159]
	v_mfma_f32_16x16x32_bf16 v[152:155], v[104:107], v[164:167], v[152:155]
	v_mfma_f32_16x16x32_bf16 v[132:135], v[84:87], v[172:175], v[132:135]
	v_mfma_f32_16x16x32_bf16 v[128:131], v[104:107], v[172:175], v[128:131]
	v_mfma_f32_16x16x32_bf16 v[108:111], v[84:87], v[180:183], v[108:111]
	v_mfma_f32_16x16x32_bf16 v[100:103], v[104:107], v[180:183], v[100:103]
	v_mfma_f32_16x16x32_bf16 v[80:83], v[84:87], v[188:191], v[80:83]
	v_mfma_f32_16x16x32_bf16 v[76:79], v[104:107], v[188:191], v[76:79]
	v_mfma_f32_16x16x32_bf16 v[156:159], v[88:91], v[168:171], v[156:159]
	v_mfma_f32_16x16x32_bf16 v[152:155], v[112:115], v[168:171], v[152:155]
	v_mfma_f32_16x16x32_bf16 v[132:135], v[88:91], v[176:179], v[132:135]
	v_mfma_f32_16x16x32_bf16 v[128:131], v[112:115], v[176:179], v[128:131]
	v_mfma_f32_16x16x32_bf16 v[108:111], v[88:91], v[184:187], v[108:111]
	v_mfma_f32_16x16x32_bf16 v[100:103], v[112:115], v[184:187], v[100:103]
	v_mfma_f32_16x16x32_bf16 v[80:83], v[88:91], v[192:195], v[80:83]
	v_mfma_f32_16x16x32_bf16 v[76:79], v[112:115], v[192:195], v[76:79]
	v_mfma_f32_16x16x32_bf16 v[144:147], v[124:127], v[164:167], v[144:147]
	v_mfma_f32_16x16x32_bf16 v[140:143], v[148:151], v[164:167], v[140:143]
	v_mfma_f32_16x16x32_bf16 v[120:123], v[124:127], v[172:175], v[120:123]
	v_mfma_f32_16x16x32_bf16 v[116:119], v[148:151], v[172:175], v[116:119]
	v_mfma_f32_16x16x32_bf16 v[96:99], v[124:127], v[180:183], v[96:99]
	v_mfma_f32_16x16x32_bf16 v[92:95], v[148:151], v[180:183], v[92:95]
	v_mfma_f32_16x16x32_bf16 v[72:75], v[124:127], v[188:191], v[72:75]
	v_mfma_f32_16x16x32_bf16 v[68:71], v[148:151], v[188:191], v[68:71]
	v_mfma_f32_16x16x32_bf16 v[144:147], v[136:139], v[168:171], v[144:147]
	v_mfma_f32_16x16x32_bf16 v[140:143], v[160:163], v[168:171], v[140:143]
	v_mfma_f32_16x16x32_bf16 v[120:123], v[136:139], v[176:179], v[120:123]
	v_mfma_f32_16x16x32_bf16 v[116:119], v[160:163], v[176:179], v[116:119]
	v_mfma_f32_16x16x32_bf16 v[96:99], v[136:139], v[184:187], v[96:99]
	v_mfma_f32_16x16x32_bf16 v[92:95], v[160:163], v[184:187], v[92:95]
	v_mfma_f32_16x16x32_bf16 v[72:75], v[136:139], v[192:195], v[72:75]
	v_mfma_f32_16x16x32_bf16 v[68:71], v[160:163], v[192:195], v[68:71]
	s_barrier
	s_add_i32 s83, s83, s23
	s_mov_b32 m0, s83
	ds_read_b128 v[164:167], v231 offset:16384
	ds_read_b128 v[168:171], v231 offset:17408
	ds_read_b128 v[172:175], v231 offset:18432
	ds_read_b128 v[176:179], v231 offset:19456
	global_load_lds_dwordx4 v2, s[52:53]
	s_add_i32 m0, s83, 0x2000
	s_add_u32 s86, s52, 0x80000
	s_addc_u32 s87, s53, 0
	s_add_i32 s83, s85, s23
	global_load_lds_dwordx4 v208, s[52:53]
	s_mov_b32 m0, s83
	ds_read_b128 v[192:195], v231 offset:23552
	global_load_lds_dwordx4 v2, s[86:87]
	s_add_i32 m0, s83, 0x2000
	ds_read_b128 v[188:191], v231 offset:22528
	global_load_lds_dwordx4 v208, s[86:87]
	s_add_u32 s98, s54, 0x80
	s_addc_u32 s99, s55, 0
	s_mov_b32 m0, s26
	ds_read_b128 v[184:187], v231 offset:21504
	global_load_lds_dwordx4 v204, s[54:55]
	s_mov_b32 m0, s27
	ds_read_b128 v[180:183], v231 offset:20480
	global_load_lds_dwordx4 v206, s[54:55]
	s_waitcnt vmcnt(8) lgkmcnt(0)
	s_barrier
	v_mfma_f32_16x16x32_bf16 v[64:67], v[84:87], v[164:167], v[64:67]
	v_mfma_f32_16x16x32_bf16 v[60:63], v[104:107], v[164:167], v[60:63]
	v_mfma_f32_16x16x32_bf16 v[48:51], v[84:87], v[172:175], v[48:51]
	v_mfma_f32_16x16x32_bf16 v[44:47], v[104:107], v[172:175], v[44:47]
	v_mfma_f32_16x16x32_bf16 v[32:35], v[84:87], v[180:183], v[32:35]
	v_mfma_f32_16x16x32_bf16 v[28:31], v[104:107], v[180:183], v[28:31]
	v_mfma_f32_16x16x32_bf16 v[16:19], v[84:87], v[188:191], v[16:19]
	v_mfma_f32_16x16x32_bf16 v[12:15], v[104:107], v[188:191], v[12:15]
	v_mfma_f32_16x16x32_bf16 v[64:67], v[88:91], v[168:171], v[64:67]
	v_mfma_f32_16x16x32_bf16 v[60:63], v[112:115], v[168:171], v[60:63]
	v_mfma_f32_16x16x32_bf16 v[48:51], v[88:91], v[176:179], v[48:51]
	v_mfma_f32_16x16x32_bf16 v[44:47], v[112:115], v[176:179], v[44:47]
	v_mfma_f32_16x16x32_bf16 v[32:35], v[88:91], v[184:187], v[32:35]
	v_mfma_f32_16x16x32_bf16 v[28:31], v[112:115], v[184:187], v[28:31]
	v_mfma_f32_16x16x32_bf16 v[16:19], v[88:91], v[192:195], v[16:19]
	v_mfma_f32_16x16x32_bf16 v[12:15], v[112:115], v[192:195], v[12:15]
	v_mfma_f32_16x16x32_bf16 v[56:59], v[124:127], v[164:167], v[56:59]
	v_mfma_f32_16x16x32_bf16 v[52:55], v[148:151], v[164:167], v[52:55]
	v_mfma_f32_16x16x32_bf16 v[40:43], v[124:127], v[172:175], v[40:43]
	v_mfma_f32_16x16x32_bf16 v[36:39], v[148:151], v[172:175], v[36:39]
	v_mfma_f32_16x16x32_bf16 v[24:27], v[124:127], v[180:183], v[24:27]
	v_mfma_f32_16x16x32_bf16 v[20:23], v[148:151], v[180:183], v[20:23]
	v_mfma_f32_16x16x32_bf16 v[8:11], v[124:127], v[188:191], v[8:11]
	v_mfma_f32_16x16x32_bf16 v[4:7], v[148:151], v[188:191], v[4:7]
	v_mfma_f32_16x16x32_bf16 v[56:59], v[136:139], v[168:171], v[56:59]
	v_mfma_f32_16x16x32_bf16 v[52:55], v[160:163], v[168:171], v[52:55]
	v_mfma_f32_16x16x32_bf16 v[40:43], v[136:139], v[176:179], v[40:43]
	v_mfma_f32_16x16x32_bf16 v[36:39], v[160:163], v[176:179], v[36:39]
	v_mfma_f32_16x16x32_bf16 v[24:27], v[136:139], v[184:187], v[24:27]
	v_mfma_f32_16x16x32_bf16 v[20:23], v[160:163], v[184:187], v[20:23]
	v_mfma_f32_16x16x32_bf16 v[8:11], v[136:139], v[192:195], v[8:11]
	v_mfma_f32_16x16x32_bf16 v[4:7], v[160:163], v[192:195], v[4:7]
	s_barrier
; #define PG8_STAGE(bufoff, gbase, voff) do { _Pragma("unroll") for (int _i = 0; _i < 2; ++_i) \
;         __builtin_amdgcn_global_load_lds((const unsigned*)((const char*)(gbase) + (voff)[_i]), (LAS unsigned*)(lds + (bufoff) + ldsw + _i * 8192), 16, 0, 0); } while (0)
; #define PG8_LDA(dst, b, h) do { _Pragma("unroll") for (int m = 0; m < 4; ++m) _Pragma("unroll") for (int k = 0; k < 2; ++k) dst[m][k] = *(const LAS bf16x8*)(lds + PG8_SA(b, h) + aoff + m * 2048 + k * 1024); } while (0)
; #define PG8_LDB(dst, b, h) do { _Pragma("unroll") for (int n = 0; n < 2; ++n) _Pragma("unroll") for (int k = 0; k < 2; ++k) dst[n][k] = *(const LAS bf16x8*)(lds + PG8_SB(b, h) + boff + n * 2048 + k * 1024); } while (0)
; #define PG8_MMA(ai, bj, At, Bt) do { __builtin_amdgcn_s_setprio(1); _Pragma("unroll") for (int m = 0; m < 4; ++m) _Pragma("unroll") for (int n = 0; n < 2; ++n) _Pragma("unroll") for (int k = 0; k < 2; ++k) \
;         acc[ai][bj][m][n] = __builtin_amdgcn_mfma_f32_16x16x32_bf16(Bt[n][k], At[m][k], acc[ai][bj][m][n], 0, 0, 0); __builtin_amdgcn_s_setprio(0); } while (0)
; #define PG8_WAIT_V(n) asm volatile("s_waitcnt vmcnt(" #n ")" ::: "memory")
; #define PG8_WAIT_L(n) asm volatile("s_waitcnt lgkmcnt(" #n ")" ::: "memory")
; #define PG8_BAR __builtin_amdgcn_s_barrier()
; #define PG8_SCHED __builtin_amdgcn_sched_barrier(0)
; template <class Epi, class Sched>
; DI void gemm_phase(LAS unsigned char* lds, const Sched& S, const Epi& E) {
;     ...
;             PG8_LDB(B0, 1, 0); PG8_LDB(B1, 1, 1); PG8_SCHED; PG8_LDA(At, 1, 0); PG8_STAGE(PG8_SA(0, 1), a2 + hstepA, voffA);
;             PG8_WAIT_V(8); PG8_WAIT_L(0); PG8_BAR; PG8_MMA(0, 0, At, B0); PG8_MMA(0, 1, At, B1); PG8_BAR; PG8_SCHED;
;             PG8_LDA(At, 1, 1); PG8_STAGE(PG8_SB(1, 0), b3, voffB); PG8_STAGE(PG8_SB(1, 1), b3 + hstepB, voffB); PG8_STAGE(PG8_SA(1, 0), a3, voffA);
;             PG8_WAIT_V(8); PG8_WAIT_L(0); PG8_BAR; PG8_MMA(1, 0, At, B0); PG8_MMA(1, 1, At, B1); PG8_BAR; PG8_SCHED;
;         }
;         if (wr == 0) PG8_BAR;
	s_add_i32 s83, 0, 0x18000
	s_add_i32 s85, 0, 0x1c000
	ds_read_b128 v[84:87], v214 offset:32768
	ds_read_b128 v[88:91], v214 offset:33792
	ds_read_b128 v[104:107], v214 offset:34816
	ds_read_b128 v[112:115], v214 offset:35840
	ds_read_b128 v[124:127], v214 offset:49152
	ds_read_b128 v[136:139], v214 offset:50176
	ds_read_b128 v[148:151], v214 offset:51200
	ds_read_b128 v[160:163], v214 offset:52224
	s_add_u32 s54, s54, 0x80000
	s_addc_u32 s55, s55, 0
	s_mov_b32 m0, s60
	ds_read_b128 v[164:167], v231 offset:32768
	ds_read_b128 v[168:171], v231 offset:33792
	ds_read_b128 v[172:175], v231 offset:34816
	ds_read_b128 v[176:179], v231 offset:35840
	ds_read_b128 v[180:183], v231 offset:36864
	ds_read_b128 v[184:187], v231 offset:37888
	ds_read_b128 v[188:191], v231 offset:38912
	global_load_lds_dwordx4 v204, s[54:55]
	s_mov_b32 m0, s61
	ds_read_b128 v[192:195], v231 offset:39936
	global_load_lds_dwordx4 v206, s[54:55]
	s_waitcnt vmcnt(8) lgkmcnt(0)
	s_barrier
	v_mfma_f32_16x16x32_bf16 v[156:159], v[84:87], v[164:167], v[156:159]
	v_mfma_f32_16x16x32_bf16 v[152:155], v[104:107], v[164:167], v[152:155]
	v_mfma_f32_16x16x32_bf16 v[132:135], v[84:87], v[172:175], v[132:135]
	v_mfma_f32_16x16x32_bf16 v[128:131], v[104:107], v[172:175], v[128:131]
	v_mfma_f32_16x16x32_bf16 v[108:111], v[84:87], v[180:183], v[108:111]
	v_mfma_f32_16x16x32_bf16 v[100:103], v[104:107], v[180:183], v[100:103]
	v_mfma_f32_16x16x32_bf16 v[80:83], v[84:87], v[188:191], v[80:83]
	v_mfma_f32_16x16x32_bf16 v[76:79], v[104:107], v[188:191], v[76:79]
	v_mfma_f32_16x16x32_bf16 v[156:159], v[88:91], v[168:171], v[156:159]
	v_mfma_f32_16x16x32_bf16 v[152:155], v[112:115], v[168:171], v[152:155]
	v_mfma_f32_16x16x32_bf16 v[132:135], v[88:91], v[176:179], v[132:135]
	v_mfma_f32_16x16x32_bf16 v[128:131], v[112:115], v[176:179], v[128:131]
	v_mfma_f32_16x16x32_bf16 v[108:111], v[88:91], v[184:187], v[108:111]
	v_mfma_f32_16x16x32_bf16 v[100:103], v[112:115], v[184:187], v[100:103]
	v_mfma_f32_16x16x32_bf16 v[80:83], v[88:91], v[192:195], v[80:83]
	v_mfma_f32_16x16x32_bf16 v[76:79], v[112:115], v[192:195], v[76:79]
	v_mfma_f32_16x16x32_bf16 v[144:147], v[124:127], v[164:167], v[144:147]
	v_mfma_f32_16x16x32_bf16 v[140:143], v[148:151], v[164:167], v[140:143]
	v_mfma_f32_16x16x32_bf16 v[120:123], v[124:127], v[172:175], v[120:123]
	v_mfma_f32_16x16x32_bf16 v[116:119], v[148:151], v[172:175], v[116:119]
	v_mfma_f32_16x16x32_bf16 v[96:99], v[124:127], v[180:183], v[96:99]
	v_mfma_f32_16x16x32_bf16 v[92:95], v[148:151], v[180:183], v[92:95]
	v_mfma_f32_16x16x32_bf16 v[72:75], v[124:127], v[188:191], v[72:75]
	v_mfma_f32_16x16x32_bf16 v[68:71], v[148:151], v[188:191], v[68:71]
	v_mfma_f32_16x16x32_bf16 v[144:147], v[136:139], v[168:171], v[144:147]
	v_mfma_f32_16x16x32_bf16 v[140:143], v[160:163], v[168:171], v[140:143]
	v_mfma_f32_16x16x32_bf16 v[120:123], v[136:139], v[176:179], v[120:123]
	v_mfma_f32_16x16x32_bf16 v[116:119], v[160:163], v[176:179], v[116:119]
	v_mfma_f32_16x16x32_bf16 v[96:99], v[136:139], v[184:187], v[96:99]
	v_mfma_f32_16x16x32_bf16 v[92:95], v[160:163], v[184:187], v[92:95]
	v_mfma_f32_16x16x32_bf16 v[72:75], v[136:139], v[192:195], v[72:75]
	v_mfma_f32_16x16x32_bf16 v[68:71], v[160:163], v[192:195], v[68:71]
	s_barrier
	s_add_i32 s54, s83, s23
	s_add_u32 s52, s52, 0x80
	s_addc_u32 s53, s53, 0
	s_mov_b32 m0, s54
	ds_read_b128 v[164:167], v231 offset:49152
	ds_read_b128 v[168:171], v231 offset:50176
	ds_read_b128 v[172:175], v231 offset:51200
	ds_read_b128 v[176:179], v231 offset:52224
	global_load_lds_dwordx4 v2, s[52:53]
	s_add_i32 m0, s54, 0x2000
	s_add_i32 s54, s85, s23
	global_load_lds_dwordx4 v208, s[52:53]
	s_add_u32 s52, s52, 0x80000
	s_addc_u32 s53, s53, 0
	s_mov_b32 m0, s54
	ds_read_b128 v[192:195], v231 offset:56320
	global_load_lds_dwordx4 v2, s[52:53]
	s_add_i32 m0, s54, 0x2000
	ds_read_b128 v[188:191], v231 offset:55296
	global_load_lds_dwordx4 v208, s[52:53]
	s_mov_b32 m0, s71
	ds_read_b128 v[184:187], v231 offset:54272
	global_load_lds_dwordx4 v204, s[98:99]
	s_mov_b32 m0, s72
	ds_read_b128 v[180:183], v231 offset:53248
	global_load_lds_dwordx4 v206, s[98:99]
	s_waitcnt vmcnt(8) lgkmcnt(0)
	s_barrier
	v_mfma_f32_16x16x32_bf16 v[64:67], v[84:87], v[164:167], v[64:67]
	v_mfma_f32_16x16x32_bf16 v[60:63], v[104:107], v[164:167], v[60:63]
	v_mfma_f32_16x16x32_bf16 v[48:51], v[84:87], v[172:175], v[48:51]
	v_mfma_f32_16x16x32_bf16 v[44:47], v[104:107], v[172:175], v[44:47]
	v_mfma_f32_16x16x32_bf16 v[32:35], v[84:87], v[180:183], v[32:35]
	v_mfma_f32_16x16x32_bf16 v[28:31], v[104:107], v[180:183], v[28:31]
	v_mfma_f32_16x16x32_bf16 v[16:19], v[84:87], v[188:191], v[16:19]
	v_mfma_f32_16x16x32_bf16 v[12:15], v[104:107], v[188:191], v[12:15]
	v_mfma_f32_16x16x32_bf16 v[64:67], v[88:91], v[168:171], v[64:67]
	v_mfma_f32_16x16x32_bf16 v[60:63], v[112:115], v[168:171], v[60:63]
	v_mfma_f32_16x16x32_bf16 v[48:51], v[88:91], v[176:179], v[48:51]
	v_mfma_f32_16x16x32_bf16 v[44:47], v[112:115], v[176:179], v[44:47]
	v_mfma_f32_16x16x32_bf16 v[32:35], v[88:91], v[184:187], v[32:35]
	v_mfma_f32_16x16x32_bf16 v[28:31], v[112:115], v[184:187], v[28:31]
	v_mfma_f32_16x16x32_bf16 v[16:19], v[88:91], v[192:195], v[16:19]
	v_mfma_f32_16x16x32_bf16 v[12:15], v[112:115], v[192:195], v[12:15]
	v_mfma_f32_16x16x32_bf16 v[56:59], v[124:127], v[164:167], v[56:59]
	v_mfma_f32_16x16x32_bf16 v[52:55], v[148:151], v[164:167], v[52:55]
	v_mfma_f32_16x16x32_bf16 v[40:43], v[124:127], v[172:175], v[40:43]
	v_mfma_f32_16x16x32_bf16 v[36:39], v[148:151], v[172:175], v[36:39]
	v_mfma_f32_16x16x32_bf16 v[24:27], v[124:127], v[180:183], v[24:27]
	v_mfma_f32_16x16x32_bf16 v[20:23], v[148:151], v[180:183], v[20:23]
	v_mfma_f32_16x16x32_bf16 v[8:11], v[124:127], v[188:191], v[8:11]
	v_mfma_f32_16x16x32_bf16 v[4:7], v[148:151], v[188:191], v[4:7]
	v_mfma_f32_16x16x32_bf16 v[56:59], v[136:139], v[168:171], v[56:59]
	v_mfma_f32_16x16x32_bf16 v[52:55], v[160:163], v[168:171], v[52:55]
	v_mfma_f32_16x16x32_bf16 v[40:43], v[136:139], v[176:179], v[40:43]
	v_mfma_f32_16x16x32_bf16 v[36:39], v[160:163], v[176:179], v[36:39]
	v_mfma_f32_16x16x32_bf16 v[24:27], v[136:139], v[184:187], v[24:27]
	v_mfma_f32_16x16x32_bf16 v[20:23], v[160:163], v[184:187], v[20:23]
	v_mfma_f32_16x16x32_bf16 v[8:11], v[136:139], v[192:195], v[8:11]
	v_mfma_f32_16x16x32_bf16 v[4:7], v[160:163], v[192:195], v[4:7]
	s_barrier
	s_add_u32 s80, s80, 0x100
	s_addc_u32 s81, s81, 0
	s_add_u32 s42, s42, 0x100
	s_addc_u32 s43, s43, 0
	s_cmp_ge_i32 s82, s75
	s_mov_b32 s52, s82
	s_cbranch_scc0 .LBB0_1104
	s_and_b64 vcc, exec, s[38:39]
	s_cbranch_vccz .LBB0_1107
	s_barrier

; #define PG8_STAGE(bufoff, gbase, voff) do { _Pragma("unroll") for (int _i = 0; _i < 2; ++_i) \
;         __builtin_amdgcn_global_load_lds((const unsigned*)((const char*)(gbase) + (voff)[_i]), (LAS unsigned*)(lds + (bufoff) + ldsw + _i * 8192), 16, 0, 0); } while (0)
; #define PG8_LDA(dst, b, h) do { _Pragma("unroll") for (int m = 0; m < 4; ++m) _Pragma("unroll") for (int k = 0; k < 2; ++k) dst[m][k] = *(const LAS bf16x8*)(lds + PG8_SA(b, h) + aoff + m * 2048 + k * 1024); } while (0)
; #define PG8_LDB(dst, b, h) do { _Pragma("unroll") for (int n = 0; n < 2; ++n) _Pragma("unroll") for (int k = 0; k < 2; ++k) dst[n][k] = *(const LAS bf16x8*)(lds + PG8_SB(b, h) + boff + n * 2048 + k * 1024); } while (0)
; #define PG8_MMA(ai, bj, At, Bt) do { __builtin_amdgcn_s_setprio(1); _Pragma("unroll") for (int m = 0; m < 4; ++m) _Pragma("unroll") for (int n = 0; n < 2; ++n) _Pragma("unroll") for (int k = 0; k < 2; ++k) \
;         acc[ai][bj][m][n] = __builtin_amdgcn_mfma_f32_16x16x32_bf16(Bt[n][k], At[m][k], acc[ai][bj][m][n], 0, 0, 0); __builtin_amdgcn_s_setprio(0); } while (0)
; #define PG8_WAIT_V(n) asm volatile("s_waitcnt vmcnt(" #n ")" ::: "memory")
; #define PG8_WAIT_L(n) asm volatile("s_waitcnt lgkmcnt(" #n ")" ::: "memory")
; #define PG8_BAR __builtin_amdgcn_s_barrier()
; template <class Epi, class Sched>
; DI void gemm_phase(LAS unsigned char* lds, const Sched& S, const Epi& E) {
;     ...
;         for (int t = 0; t < nt; t += 2) {
;             const bool last = (t == nt - 2);
;             const char* a1 = cA + (size_t)(t + 1) * kstep;
;             const char* a2 = last ? nA : cA + (size_t)(t + 2) * kstep; const char* b2 = last ? nB : cB + (size_t)(t + 2) * kstep;
;             const char* a3 = a2 + kstep; const char* b3 = b2 + kstep;
;             if constexpr (Epi::HOOK) { if (cur.ks < 0 && (t == 16 || t == 32)) E.hook(acc, cur, t >> 4, wr, wc, fr, fq); }
;             PG8_LDB(B0, 0, 0); PG8_LDB(B1, 0, 1); PG8_SCHED; PG8_LDA(At, 0, 0); PG8_STAGE(PG8_SA(1, 1), a1 + hstepA, voffA);
;             PG8_WAIT_V(8); PG8_WAIT_L(0); PG8_BAR; PG8_MMA(0, 0, At, B0); PG8_MMA(0, 1, At, B1); PG8_BAR; PG8_SCHED;
;             PG8_LDA(At, 0, 1); PG8_STAGE(PG8_SB(0, 0), b2, voffB); PG8_STAGE(PG8_SB(0, 1), b2 + hstepB, voffB); PG8_STAGE(PG8_SA(0, 0), a2, voffA);
;             PG8_WAIT_V(8); PG8_WAIT_L(0); PG8_BAR; PG8_MMA(1, 0, At, B0); PG8_MMA(1, 1, At, B1); PG8_BAR; PG8_SCHED;
.LBB0_1184:
	v_add_u32_e32 v194, 0x10000, v146
	s_add_i32 s85, s54, 2
	s_add_u32 s55, s42, 0xfff80080
	s_addc_u32 s56, s43, -1
	s_add_i32 s86, 0, 0x10000
	s_cmp_eq_u32 s81, s54
	s_cselect_b32 s57, s58, s56
	s_cselect_b32 s56, s59, s55
	s_cselect_b32 s55, s60, s83
	s_cselect_b32 s54, s61, s82
	s_add_i32 s88, 0, 0x14000
	ds_read_b128 v[142:145], v194
	ds_read_b128 v[150:153], v194 offset:1024
	ds_read_b128 v[154:157], v194 offset:2048
	ds_read_b128 v[158:161], v194 offset:3072
	ds_read_b128 v[162:165], v194 offset:16384
	ds_read_b128 v[166:169], v194 offset:17408
	ds_read_b128 v[170:173], v194 offset:18432
	ds_read_b128 v[174:177], v194 offset:19456
	s_add_i32 m0, s26, 0xc000
	ds_read_b128 v[178:181], v148
	ds_read_b128 v[182:185], v148 offset:1024
	ds_read_b128 v[186:189], v148 offset:2048
	ds_read_b128 v[190:193], v148 offset:3072
	ds_read_b128 v[204:207], v148 offset:4096
	ds_read_b128 v[208:211], v148 offset:5120
	ds_read_b128 v[212:215], v148 offset:6144
	global_load_lds_dwordx4 v140, s[42:43]
	s_add_i32 m0, s26, 0xe000
	ds_read_b128 v[230:233], v148 offset:7168
	global_load_lds_dwordx4 v138, s[42:43]
	s_waitcnt vmcnt(8) lgkmcnt(0)
	s_barrier
	v_mfma_f32_16x16x32_bf16 v[128:131], v[142:145], v[178:181], v[128:131]
	v_mfma_f32_16x16x32_bf16 v[124:127], v[154:157], v[178:181], v[124:127]
	v_mfma_f32_16x16x32_bf16 v[112:115], v[142:145], v[186:189], v[112:115]
	v_mfma_f32_16x16x32_bf16 v[108:111], v[154:157], v[186:189], v[108:111]
	v_mfma_f32_16x16x32_bf16 v[96:99], v[142:145], v[204:207], v[96:99]
	v_mfma_f32_16x16x32_bf16 v[92:95], v[154:157], v[204:207], v[92:95]
	v_mfma_f32_16x16x32_bf16 v[80:83], v[142:145], v[212:215], v[80:83]
	v_mfma_f32_16x16x32_bf16 v[76:79], v[154:157], v[212:215], v[76:79]
	v_mfma_f32_16x16x32_bf16 v[128:131], v[150:153], v[182:185], v[128:131]
	v_mfma_f32_16x16x32_bf16 v[124:127], v[158:161], v[182:185], v[124:127]
	v_mfma_f32_16x16x32_bf16 v[112:115], v[150:153], v[190:193], v[112:115]
	v_mfma_f32_16x16x32_bf16 v[108:111], v[158:161], v[190:193], v[108:111]
	v_mfma_f32_16x16x32_bf16 v[96:99], v[150:153], v[208:211], v[96:99]
	v_mfma_f32_16x16x32_bf16 v[92:95], v[158:161], v[208:211], v[92:95]
	v_mfma_f32_16x16x32_bf16 v[80:83], v[150:153], v[230:233], v[80:83]
	v_mfma_f32_16x16x32_bf16 v[76:79], v[158:161], v[230:233], v[76:79]
	v_mfma_f32_16x16x32_bf16 v[120:123], v[162:165], v[178:181], v[120:123]
	v_mfma_f32_16x16x32_bf16 v[116:119], v[170:173], v[178:181], v[116:119]
	v_mfma_f32_16x16x32_bf16 v[104:107], v[162:165], v[186:189], v[104:107]
	v_mfma_f32_16x16x32_bf16 v[100:103], v[170:173], v[186:189], v[100:103]
	v_mfma_f32_16x16x32_bf16 v[88:91], v[162:165], v[204:207], v[88:91]
	v_mfma_f32_16x16x32_bf16 v[84:87], v[170:173], v[204:207], v[84:87]
	v_mfma_f32_16x16x32_bf16 v[72:75], v[162:165], v[212:215], v[72:75]
	v_mfma_f32_16x16x32_bf16 v[68:71], v[170:173], v[212:215], v[68:71]
	v_mfma_f32_16x16x32_bf16 v[120:123], v[166:169], v[182:185], v[120:123]
	v_mfma_f32_16x16x32_bf16 v[116:119], v[174:177], v[182:185], v[116:119]
	v_mfma_f32_16x16x32_bf16 v[104:107], v[166:169], v[190:193], v[104:107]
	v_mfma_f32_16x16x32_bf16 v[100:103], v[174:177], v[190:193], v[100:103]
	v_mfma_f32_16x16x32_bf16 v[88:91], v[166:169], v[208:211], v[88:91]
	v_mfma_f32_16x16x32_bf16 v[84:87], v[174:177], v[208:211], v[84:87]
	v_mfma_f32_16x16x32_bf16 v[72:75], v[166:169], v[230:233], v[72:75]
	v_mfma_f32_16x16x32_bf16 v[68:71], v[174:177], v[230:233], v[68:71]
	s_barrier
	s_add_i32 s86, s86, s23
	s_mov_b32 m0, s86
	ds_read_b128 v[178:181], v148 offset:16384
	ds_read_b128 v[182:185], v148 offset:17408
	ds_read_b128 v[186:189], v148 offset:18432
	ds_read_b128 v[190:193], v148 offset:19456
	global_load_lds_dwordx4 v2, s[54:55]
	s_add_i32 m0, s86, 0x2000
	s_add_u32 s86, s54, 0x80000
	s_addc_u32 s87, s55, 0
	s_add_i32 s88, s88, s23
	global_load_lds_dwordx4 v136, s[54:55]
	s_mov_b32 m0, s88
	ds_read_b128 v[230:233], v148 offset:23552
	global_load_lds_dwordx4 v2, s[86:87]
	s_add_i32 m0, s88, 0x2000
	ds_read_b128 v[212:215], v148 offset:22528
	global_load_lds_dwordx4 v136, s[86:87]
	s_add_u32 s98, s56, 0x80
	s_addc_u32 s99, s57, 0
	s_mov_b32 m0, s26
	ds_read_b128 v[208:211], v148 offset:21504
	global_load_lds_dwordx4 v132, s[56:57]
	s_mov_b32 m0, s27
	ds_read_b128 v[204:207], v148 offset:20480
	global_load_lds_dwordx4 v134, s[56:57]
	s_waitcnt vmcnt(8) lgkmcnt(0)
	s_barrier
	v_mfma_f32_16x16x32_bf16 v[64:67], v[142:145], v[178:181], v[64:67]
	v_mfma_f32_16x16x32_bf16 v[60:63], v[154:157], v[178:181], v[60:63]
	v_mfma_f32_16x16x32_bf16 v[48:51], v[142:145], v[186:189], v[48:51]
	v_mfma_f32_16x16x32_bf16 v[44:47], v[154:157], v[186:189], v[44:47]
	v_mfma_f32_16x16x32_bf16 v[32:35], v[142:145], v[204:207], v[32:35]
	v_mfma_f32_16x16x32_bf16 v[28:31], v[154:157], v[204:207], v[28:31]
	v_mfma_f32_16x16x32_bf16 v[16:19], v[142:145], v[212:215], v[16:19]
	v_mfma_f32_16x16x32_bf16 v[12:15], v[154:157], v[212:215], v[12:15]
	v_mfma_f32_16x16x32_bf16 v[64:67], v[150:153], v[182:185], v[64:67]
	v_mfma_f32_16x16x32_bf16 v[60:63], v[158:161], v[182:185], v[60:63]
	v_mfma_f32_16x16x32_bf16 v[48:51], v[150:153], v[190:193], v[48:51]
	v_mfma_f32_16x16x32_bf16 v[44:47], v[158:161], v[190:193], v[44:47]
	v_mfma_f32_16x16x32_bf16 v[32:35], v[150:153], v[208:211], v[32:35]
	v_mfma_f32_16x16x32_bf16 v[28:31], v[158:161], v[208:211], v[28:31]
	v_mfma_f32_16x16x32_bf16 v[16:19], v[150:153], v[230:233], v[16:19]
	v_mfma_f32_16x16x32_bf16 v[12:15], v[158:161], v[230:233], v[12:15]
	v_mfma_f32_16x16x32_bf16 v[56:59], v[162:165], v[178:181], v[56:59]
	v_mfma_f32_16x16x32_bf16 v[52:55], v[170:173], v[178:181], v[52:55]
	v_mfma_f32_16x16x32_bf16 v[40:43], v[162:165], v[186:189], v[40:43]
	v_mfma_f32_16x16x32_bf16 v[36:39], v[170:173], v[186:189], v[36:39]
	v_mfma_f32_16x16x32_bf16 v[24:27], v[162:165], v[204:207], v[24:27]
	v_mfma_f32_16x16x32_bf16 v[20:23], v[170:173], v[204:207], v[20:23]
	v_mfma_f32_16x16x32_bf16 v[8:11], v[162:165], v[212:215], v[8:11]
	v_mfma_f32_16x16x32_bf16 v[4:7], v[170:173], v[212:215], v[4:7]
	v_mfma_f32_16x16x32_bf16 v[56:59], v[166:169], v[182:185], v[56:59]
	v_mfma_f32_16x16x32_bf16 v[52:55], v[174:177], v[182:185], v[52:55]
	v_mfma_f32_16x16x32_bf16 v[40:43], v[166:169], v[190:193], v[40:43]
	v_mfma_f32_16x16x32_bf16 v[36:39], v[174:177], v[190:193], v[36:39]
	v_mfma_f32_16x16x32_bf16 v[24:27], v[166:169], v[208:211], v[24:27]
	v_mfma_f32_16x16x32_bf16 v[20:23], v[174:177], v[208:211], v[20:23]
	v_mfma_f32_16x16x32_bf16 v[8:11], v[166:169], v[230:233], v[8:11]
	v_mfma_f32_16x16x32_bf16 v[4:7], v[174:177], v[230:233], v[4:7]
	s_barrier
; #define PG8_STAGE(bufoff, gbase, voff) do { _Pragma("unroll") for (int _i = 0; _i < 2; ++_i) \
;         __builtin_amdgcn_global_load_lds((const unsigned*)((const char*)(gbase) + (voff)[_i]), (LAS unsigned*)(lds + (bufoff) + ldsw + _i * 8192), 16, 0, 0); } while (0)
; #define PG8_LDA(dst, b, h) do { _Pragma("unroll") for (int m = 0; m < 4; ++m) _Pragma("unroll") for (int k = 0; k < 2; ++k) dst[m][k] = *(const LAS bf16x8*)(lds + PG8_SA(b, h) + aoff + m * 2048 + k * 1024); } while (0)
; #define PG8_LDB(dst, b, h) do { _Pragma("unroll") for (int n = 0; n < 2; ++n) _Pragma("unroll") for (int k = 0; k < 2; ++k) dst[n][k] = *(const LAS bf16x8*)(lds + PG8_SB(b, h) + boff + n * 2048 + k * 1024); } while (0)
; #define PG8_MMA(ai, bj, At, Bt) do { __builtin_amdgcn_s_setprio(1); _Pragma("unroll") for (int m = 0; m < 4; ++m) _Pragma("unroll") for (int n = 0; n < 2; ++n) _Pragma("unroll") for (int k = 0; k < 2; ++k) \
;         acc[ai][bj][m][n] = __builtin_amdgcn_mfma_f32_16x16x32_bf16(Bt[n][k], At[m][k], acc[ai][bj][m][n], 0, 0, 0); __builtin_amdgcn_s_setprio(0); } while (0)
; #define PG8_WAIT_V(n) asm volatile("s_waitcnt vmcnt(" #n ")" ::: "memory")
; #define PG8_WAIT_L(n) asm volatile("s_waitcnt lgkmcnt(" #n ")" ::: "memory")
; #define PG8_BAR __builtin_amdgcn_s_barrier()
; #define PG8_SCHED __builtin_amdgcn_sched_barrier(0)
; template <class Epi, class Sched>
; DI void gemm_phase(LAS unsigned char* lds, const Sched& S, const Epi& E) {
;     ...
;             PG8_LDB(B0, 1, 0); PG8_LDB(B1, 1, 1); PG8_SCHED; PG8_LDA(At, 1, 0); PG8_STAGE(PG8_SA(0, 1), a2 + hstepA, voffA);
;             PG8_WAIT_V(8); PG8_WAIT_L(0); PG8_BAR; PG8_MMA(0, 0, At, B0); PG8_MMA(0, 1, At, B1); PG8_BAR; PG8_SCHED;
;             PG8_LDA(At, 1, 1); PG8_STAGE(PG8_SB(1, 0), b3, voffB); PG8_STAGE(PG8_SB(1, 1), b3 + hstepB, voffB); PG8_STAGE(PG8_SA(1, 0), a3, voffA);
;             PG8_WAIT_V(8); PG8_WAIT_L(0); PG8_BAR; PG8_MMA(1, 0, At, B0); PG8_MMA(1, 1, At, B1); PG8_BAR; PG8_SCHED;
;         }
;         if (wr == 0) PG8_BAR;
	s_add_i32 s86, 0, 0x18000
	s_add_i32 s87, 0, 0x1c000
	ds_read_b128 v[142:145], v194 offset:32768
	ds_read_b128 v[150:153], v194 offset:33792
	ds_read_b128 v[154:157], v194 offset:34816
	ds_read_b128 v[158:161], v194 offset:35840
	ds_read_b128 v[162:165], v194 offset:49152
	ds_read_b128 v[166:169], v194 offset:50176
	ds_read_b128 v[170:173], v194 offset:51200
	ds_read_b128 v[174:177], v194 offset:52224
	s_add_u32 s56, s56, 0x80000
	s_addc_u32 s57, s57, 0
	s_mov_b32 m0, s65
	ds_read_b128 v[178:181], v148 offset:32768
	ds_read_b128 v[182:185], v148 offset:33792
	ds_read_b128 v[186:189], v148 offset:34816
	ds_read_b128 v[190:193], v148 offset:35840
	ds_read_b128 v[204:207], v148 offset:36864
	ds_read_b128 v[208:211], v148 offset:37888
	ds_read_b128 v[212:215], v148 offset:38912
	global_load_lds_dwordx4 v132, s[56:57]
	s_mov_b32 m0, s66
	ds_read_b128 v[230:233], v148 offset:39936
	global_load_lds_dwordx4 v134, s[56:57]
	s_waitcnt vmcnt(8) lgkmcnt(0)
	s_barrier
	v_mfma_f32_16x16x32_bf16 v[128:131], v[142:145], v[178:181], v[128:131]
	v_mfma_f32_16x16x32_bf16 v[124:127], v[154:157], v[178:181], v[124:127]
	v_mfma_f32_16x16x32_bf16 v[112:115], v[142:145], v[186:189], v[112:115]
	v_mfma_f32_16x16x32_bf16 v[108:111], v[154:157], v[186:189], v[108:111]
	v_mfma_f32_16x16x32_bf16 v[96:99], v[142:145], v[204:207], v[96:99]
	v_mfma_f32_16x16x32_bf16 v[92:95], v[154:157], v[204:207], v[92:95]
	v_mfma_f32_16x16x32_bf16 v[80:83], v[142:145], v[212:215], v[80:83]
	v_mfma_f32_16x16x32_bf16 v[76:79], v[154:157], v[212:215], v[76:79]
	v_mfma_f32_16x16x32_bf16 v[128:131], v[150:153], v[182:185], v[128:131]
	v_mfma_f32_16x16x32_bf16 v[124:127], v[158:161], v[182:185], v[124:127]
	v_mfma_f32_16x16x32_bf16 v[112:115], v[150:153], v[190:193], v[112:115]
	v_mfma_f32_16x16x32_bf16 v[108:111], v[158:161], v[190:193], v[108:111]
	v_mfma_f32_16x16x32_bf16 v[96:99], v[150:153], v[208:211], v[96:99]
	v_mfma_f32_16x16x32_bf16 v[92:95], v[158:161], v[208:211], v[92:95]
	v_mfma_f32_16x16x32_bf16 v[80:83], v[150:153], v[230:233], v[80:83]
	v_mfma_f32_16x16x32_bf16 v[76:79], v[158:161], v[230:233], v[76:79]
	v_mfma_f32_16x16x32_bf16 v[120:123], v[162:165], v[178:181], v[120:123]
	v_mfma_f32_16x16x32_bf16 v[116:119], v[170:173], v[178:181], v[116:119]
	v_mfma_f32_16x16x32_bf16 v[104:107], v[162:165], v[186:189], v[104:107]
	v_mfma_f32_16x16x32_bf16 v[100:103], v[170:173], v[186:189], v[100:103]
	v_mfma_f32_16x16x32_bf16 v[88:91], v[162:165], v[204:207], v[88:91]
	v_mfma_f32_16x16x32_bf16 v[84:87], v[170:173], v[204:207], v[84:87]
	v_mfma_f32_16x16x32_bf16 v[72:75], v[162:165], v[212:215], v[72:75]
	v_mfma_f32_16x16x32_bf16 v[68:71], v[170:173], v[212:215], v[68:71]
	v_mfma_f32_16x16x32_bf16 v[120:123], v[166:169], v[182:185], v[120:123]
	v_mfma_f32_16x16x32_bf16 v[116:119], v[174:177], v[182:185], v[116:119]
	v_mfma_f32_16x16x32_bf16 v[104:107], v[166:169], v[190:193], v[104:107]
	v_mfma_f32_16x16x32_bf16 v[100:103], v[174:177], v[190:193], v[100:103]
	v_mfma_f32_16x16x32_bf16 v[88:91], v[166:169], v[208:211], v[88:91]
	v_mfma_f32_16x16x32_bf16 v[84:87], v[174:177], v[208:211], v[84:87]
	v_mfma_f32_16x16x32_bf16 v[72:75], v[166:169], v[230:233], v[72:75]
	v_mfma_f32_16x16x32_bf16 v[68:71], v[174:177], v[230:233], v[68:71]
	s_barrier
	s_add_i32 s56, s86, s23
	s_add_u32 s54, s54, 0x80
	s_addc_u32 s55, s55, 0
	s_mov_b32 m0, s56
	ds_read_b128 v[178:181], v148 offset:49152
	ds_read_b128 v[182:185], v148 offset:50176
	ds_read_b128 v[186:189], v148 offset:51200
	ds_read_b128 v[190:193], v148 offset:52224
	global_load_lds_dwordx4 v2, s[54:55]
	s_add_i32 m0, s56, 0x2000
	s_add_i32 s56, s87, s23
	global_load_lds_dwordx4 v136, s[54:55]
	s_add_u32 s54, s54, 0x80000
	s_addc_u32 s55, s55, 0
	s_mov_b32 m0, s56
	ds_read_b128 v[230:233], v148 offset:56320
	global_load_lds_dwordx4 v2, s[54:55]
	s_add_i32 m0, s56, 0x2000
	ds_read_b128 v[212:215], v148 offset:55296
	global_load_lds_dwordx4 v136, s[54:55]
	s_mov_b32 m0, s73
	ds_read_b128 v[208:211], v148 offset:54272
	global_load_lds_dwordx4 v132, s[98:99]
	s_mov_b32 m0, s74
	ds_read_b128 v[204:207], v148 offset:53248
	global_load_lds_dwordx4 v134, s[98:99]
	s_waitcnt vmcnt(8) lgkmcnt(0)
	s_barrier
	v_mfma_f32_16x16x32_bf16 v[64:67], v[142:145], v[178:181], v[64:67]
	v_mfma_f32_16x16x32_bf16 v[60:63], v[154:157], v[178:181], v[60:63]
	v_mfma_f32_16x16x32_bf16 v[48:51], v[142:145], v[186:189], v[48:51]
	v_mfma_f32_16x16x32_bf16 v[44:47], v[154:157], v[186:189], v[44:47]
	v_mfma_f32_16x16x32_bf16 v[32:35], v[142:145], v[204:207], v[32:35]
	v_mfma_f32_16x16x32_bf16 v[28:31], v[154:157], v[204:207], v[28:31]
	v_mfma_f32_16x16x32_bf16 v[16:19], v[142:145], v[212:215], v[16:19]
	v_mfma_f32_16x16x32_bf16 v[12:15], v[154:157], v[212:215], v[12:15]
	v_mfma_f32_16x16x32_bf16 v[64:67], v[150:153], v[182:185], v[64:67]
	v_mfma_f32_16x16x32_bf16 v[60:63], v[158:161], v[182:185], v[60:63]
	v_mfma_f32_16x16x32_bf16 v[48:51], v[150:153], v[190:193], v[48:51]
	v_mfma_f32_16x16x32_bf16 v[44:47], v[158:161], v[190:193], v[44:47]
	v_mfma_f32_16x16x32_bf16 v[32:35], v[150:153], v[208:211], v[32:35]
	v_mfma_f32_16x16x32_bf16 v[28:31], v[158:161], v[208:211], v[28:31]
	v_mfma_f32_16x16x32_bf16 v[16:19], v[150:153], v[230:233], v[16:19]
	v_mfma_f32_16x16x32_bf16 v[12:15], v[158:161], v[230:233], v[12:15]
	v_mfma_f32_16x16x32_bf16 v[56:59], v[162:165], v[178:181], v[56:59]
	v_mfma_f32_16x16x32_bf16 v[52:55], v[170:173], v[178:181], v[52:55]
	v_mfma_f32_16x16x32_bf16 v[40:43], v[162:165], v[186:189], v[40:43]
	v_mfma_f32_16x16x32_bf16 v[36:39], v[170:173], v[186:189], v[36:39]
	v_mfma_f32_16x16x32_bf16 v[24:27], v[162:165], v[204:207], v[24:27]
	v_mfma_f32_16x16x32_bf16 v[20:23], v[170:173], v[204:207], v[20:23]
	v_mfma_f32_16x16x32_bf16 v[8:11], v[162:165], v[212:215], v[8:11]
	v_mfma_f32_16x16x32_bf16 v[4:7], v[170:173], v[212:215], v[4:7]
	v_mfma_f32_16x16x32_bf16 v[56:59], v[166:169], v[182:185], v[56:59]
	v_mfma_f32_16x16x32_bf16 v[52:55], v[174:177], v[182:185], v[52:55]
	v_mfma_f32_16x16x32_bf16 v[40:43], v[166:169], v[190:193], v[40:43]
	v_mfma_f32_16x16x32_bf16 v[36:39], v[174:177], v[190:193], v[36:39]
	v_mfma_f32_16x16x32_bf16 v[24:27], v[166:169], v[208:211], v[24:27]
	v_mfma_f32_16x16x32_bf16 v[20:23], v[174:177], v[208:211], v[20:23]
	v_mfma_f32_16x16x32_bf16 v[8:11], v[166:169], v[230:233], v[8:11]
	v_mfma_f32_16x16x32_bf16 v[4:7], v[174:177], v[230:233], v[4:7]
	s_barrier
	s_add_u32 s82, s82, 0x100
	s_addc_u32 s83, s83, 0
	s_add_u32 s42, s42, 0x100
	s_addc_u32 s43, s43, 0
	s_cmp_ge_i32 s85, s79
	s_mov_b32 s54, s85
	s_cbranch_scc0 .LBB0_1184
	s_and_b64 vcc, exec, s[8:9]
	s_cbranch_vccz .LBB0_1187
	s_barrier

; #define PG8_STAGE(bufoff, gbase, voff) do { _Pragma("unroll") for (int _i = 0; _i < 2; ++_i) \
;         __builtin_amdgcn_global_load_lds((const unsigned*)((const char*)(gbase) + (voff)[_i]), (LAS unsigned*)(lds + (bufoff) + ldsw + _i * 8192), 16, 0, 0); } while (0)
; #define PG8_LDA(dst, b, h) do { _Pragma("unroll") for (int m = 0; m < 4; ++m) _Pragma("unroll") for (int k = 0; k < 2; ++k) dst[m][k] = *(const LAS bf16x8*)(lds + PG8_SA(b, h) + aoff + m * 2048 + k * 1024); } while (0)
; #define PG8_LDB(dst, b, h) do { _Pragma("unroll") for (int n = 0; n < 2; ++n) _Pragma("unroll") for (int k = 0; k < 2; ++k) dst[n][k] = *(const LAS bf16x8*)(lds + PG8_SB(b, h) + boff + n * 2048 + k * 1024); } while (0)
; #define PG8_MMA(ai, bj, At, Bt) do { __builtin_amdgcn_s_setprio(1); _Pragma("unroll") for (int m = 0; m < 4; ++m) _Pragma("unroll") for (int n = 0; n < 2; ++n) _Pragma("unroll") for (int k = 0; k < 2; ++k) \
;         acc[ai][bj][m][n] = __builtin_amdgcn_mfma_f32_16x16x32_bf16(Bt[n][k], At[m][k], acc[ai][bj][m][n], 0, 0, 0); __builtin_amdgcn_s_setprio(0); } while (0)
; #define PG8_WAIT_V(n) asm volatile("s_waitcnt vmcnt(" #n ")" ::: "memory")
; #define PG8_WAIT_L(n) asm volatile("s_waitcnt lgkmcnt(" #n ")" ::: "memory")
; #define PG8_BAR __builtin_amdgcn_s_barrier()
; template <class Epi, class Sched>
; DI void gemm_phase(LAS unsigned char* lds, const Sched& S, const Epi& E) {
;     ...
;         for (int t = 0; t < nt; t += 2) {
;             const bool last = (t == nt - 2);
;             const char* a1 = cA + (size_t)(t + 1) * kstep;
;             const char* a2 = last ? nA : cA + (size_t)(t + 2) * kstep; const char* b2 = last ? nB : cB + (size_t)(t + 2) * kstep;
;             const char* a3 = a2 + kstep; const char* b3 = b2 + kstep;
;             if constexpr (Epi::HOOK) { if (cur.ks < 0 && (t == 16 || t == 32)) E.hook(acc, cur, t >> 4, wr, wc, fr, fq); }
;             PG8_LDB(B0, 0, 0); PG8_LDB(B1, 0, 1); PG8_SCHED; PG8_LDA(At, 0, 0); PG8_STAGE(PG8_SA(1, 1), a1 + hstepA, voffA);
;             PG8_WAIT_V(8); PG8_WAIT_L(0); PG8_BAR; PG8_MMA(0, 0, At, B0); PG8_MMA(0, 1, At, B1); PG8_BAR; PG8_SCHED;
;             PG8_LDA(At, 0, 1); PG8_STAGE(PG8_SB(0, 0), b2, voffB); PG8_STAGE(PG8_SB(0, 1), b2 + hstepB, voffB); PG8_STAGE(PG8_SA(0, 0), a2, voffA);
;             PG8_WAIT_V(8); PG8_WAIT_L(0); PG8_BAR; PG8_MMA(1, 0, At, B0); PG8_MMA(1, 1, At, B1); PG8_BAR; PG8_SCHED;
.LBB0_1390:
	v_add_u32_e32 v216, 0x10000, v148
	s_add_u32 s50, s48, 0xfff80080
	s_addc_u32 s51, s49, -1
	s_add_i32 s66, 0, 0x10000
	s_cmp_eq_u32 s65, 28
	s_cselect_b32 s53, s45, s51
	s_cselect_b32 s52, s44, s50
	s_cselect_b32 s51, s47, s43
	s_cselect_b32 s50, s46, s39
	s_add_i32 s71, 0, 0x14000
	ds_read_b128 v[144:147], v216
	ds_read_b128 v[152:155], v216 offset:1024
	ds_read_b128 v[156:159], v216 offset:2048
	ds_read_b128 v[160:163], v216 offset:3072
	ds_read_b128 v[164:167], v216 offset:16384
	ds_read_b128 v[168:171], v216 offset:17408
	ds_read_b128 v[172:175], v216 offset:18432
	ds_read_b128 v[176:179], v216 offset:19456
	s_add_i32 m0, s54, 0xc000
	ds_read_b128 v[180:183], v151
	ds_read_b128 v[184:187], v151 offset:1024
	ds_read_b128 v[188:191], v151 offset:2048
	ds_read_b128 v[192:195], v151 offset:3072
	ds_read_b128 v[204:207], v151 offset:4096
	ds_read_b128 v[208:211], v151 offset:5120
	ds_read_b128 v[212:215], v151 offset:6144
	global_load_lds_dwordx4 v142, s[48:49]
	s_add_i32 m0, s54, 0xe000
	ds_read_b128 v[230:233], v151 offset:7168
	global_load_lds_dwordx4 v140, s[48:49]
	s_waitcnt vmcnt(8) lgkmcnt(0)
	s_barrier
	v_mfma_f32_16x16x32_bf16 v[128:131], v[144:147], v[180:183], v[128:131]
	v_mfma_f32_16x16x32_bf16 v[124:127], v[156:159], v[180:183], v[124:127]
	v_mfma_f32_16x16x32_bf16 v[112:115], v[144:147], v[188:191], v[112:115]
	v_mfma_f32_16x16x32_bf16 v[108:111], v[156:159], v[188:191], v[108:111]
	v_mfma_f32_16x16x32_bf16 v[96:99], v[144:147], v[204:207], v[96:99]
	v_mfma_f32_16x16x32_bf16 v[92:95], v[156:159], v[204:207], v[92:95]
	v_mfma_f32_16x16x32_bf16 v[80:83], v[144:147], v[212:215], v[80:83]
	v_mfma_f32_16x16x32_bf16 v[76:79], v[156:159], v[212:215], v[76:79]
	v_mfma_f32_16x16x32_bf16 v[128:131], v[152:155], v[184:187], v[128:131]
	v_mfma_f32_16x16x32_bf16 v[124:127], v[160:163], v[184:187], v[124:127]
	v_mfma_f32_16x16x32_bf16 v[112:115], v[152:155], v[192:195], v[112:115]
	v_mfma_f32_16x16x32_bf16 v[108:111], v[160:163], v[192:195], v[108:111]
	v_mfma_f32_16x16x32_bf16 v[96:99], v[152:155], v[208:211], v[96:99]
	v_mfma_f32_16x16x32_bf16 v[92:95], v[160:163], v[208:211], v[92:95]
	v_mfma_f32_16x16x32_bf16 v[80:83], v[152:155], v[230:233], v[80:83]
	v_mfma_f32_16x16x32_bf16 v[76:79], v[160:163], v[230:233], v[76:79]
	v_mfma_f32_16x16x32_bf16 v[120:123], v[164:167], v[180:183], v[120:123]
	v_mfma_f32_16x16x32_bf16 v[116:119], v[172:175], v[180:183], v[116:119]
	v_mfma_f32_16x16x32_bf16 v[104:107], v[164:167], v[188:191], v[104:107]
	v_mfma_f32_16x16x32_bf16 v[100:103], v[172:175], v[188:191], v[100:103]
	v_mfma_f32_16x16x32_bf16 v[88:91], v[164:167], v[204:207], v[88:91]
	v_mfma_f32_16x16x32_bf16 v[84:87], v[172:175], v[204:207], v[84:87]
	v_mfma_f32_16x16x32_bf16 v[72:75], v[164:167], v[212:215], v[72:75]
	v_mfma_f32_16x16x32_bf16 v[68:71], v[172:175], v[212:215], v[68:71]
	v_mfma_f32_16x16x32_bf16 v[120:123], v[168:171], v[184:187], v[120:123]
	v_mfma_f32_16x16x32_bf16 v[116:119], v[176:179], v[184:187], v[116:119]
	v_mfma_f32_16x16x32_bf16 v[104:107], v[168:171], v[192:195], v[104:107]
	v_mfma_f32_16x16x32_bf16 v[100:103], v[176:179], v[192:195], v[100:103]
	v_mfma_f32_16x16x32_bf16 v[88:91], v[168:171], v[208:211], v[88:91]
	v_mfma_f32_16x16x32_bf16 v[84:87], v[176:179], v[208:211], v[84:87]
	v_mfma_f32_16x16x32_bf16 v[72:75], v[168:171], v[230:233], v[72:75]
	v_mfma_f32_16x16x32_bf16 v[68:71], v[176:179], v[230:233], v[68:71]
	s_barrier
	s_add_i32 s66, s66, s27
	s_mov_b32 m0, s66
	ds_read_b128 v[180:183], v151 offset:16384
	ds_read_b128 v[184:187], v151 offset:17408
	ds_read_b128 v[188:191], v151 offset:18432
	ds_read_b128 v[192:195], v151 offset:19456
	ds_read_b128 v[204:207], v151 offset:20480
	global_load_lds_dwordx4 v2, s[50:51]
	s_add_i32 m0, s66, 0x2000
	s_add_u32 s66, s50, 0x80000
	s_addc_u32 s67, s51, 0
	s_add_i32 s71, s71, s27
	global_load_lds_dwordx4 v136, s[50:51]
	s_mov_b32 m0, s71
	s_add_u32 s86, s52, 0x80
	s_addc_u32 s87, s53, 0
	global_load_lds_dwordx4 v2, s[66:67]
	s_add_i32 m0, s71, 0x2000
	ds_read_b128 v[230:233], v151 offset:23552
	global_load_lds_dwordx4 v136, s[66:67]
	s_mov_b32 m0, s54
	ds_read_b128 v[212:215], v151 offset:22528
	global_load_lds_dwordx4 v132, s[52:53]
	s_mov_b32 m0, s55
	ds_read_b128 v[208:211], v151 offset:21504
	global_load_lds_dwordx4 v134, s[52:53]
	s_waitcnt vmcnt(8) lgkmcnt(0)
	s_barrier
	v_mfma_f32_16x16x32_bf16 v[64:67], v[144:147], v[180:183], v[64:67]
	v_mfma_f32_16x16x32_bf16 v[60:63], v[156:159], v[180:183], v[60:63]
	v_mfma_f32_16x16x32_bf16 v[48:51], v[144:147], v[188:191], v[48:51]
	v_mfma_f32_16x16x32_bf16 v[44:47], v[156:159], v[188:191], v[44:47]
	v_mfma_f32_16x16x32_bf16 v[32:35], v[144:147], v[204:207], v[32:35]
	v_mfma_f32_16x16x32_bf16 v[28:31], v[156:159], v[204:207], v[28:31]
	v_mfma_f32_16x16x32_bf16 v[16:19], v[144:147], v[212:215], v[16:19]
	v_mfma_f32_16x16x32_bf16 v[12:15], v[156:159], v[212:215], v[12:15]
	v_mfma_f32_16x16x32_bf16 v[64:67], v[152:155], v[184:187], v[64:67]
	v_mfma_f32_16x16x32_bf16 v[60:63], v[160:163], v[184:187], v[60:63]
	v_mfma_f32_16x16x32_bf16 v[48:51], v[152:155], v[192:195], v[48:51]
	v_mfma_f32_16x16x32_bf16 v[44:47], v[160:163], v[192:195], v[44:47]
	v_mfma_f32_16x16x32_bf16 v[32:35], v[152:155], v[208:211], v[32:35]
	v_mfma_f32_16x16x32_bf16 v[28:31], v[160:163], v[208:211], v[28:31]
	v_mfma_f32_16x16x32_bf16 v[16:19], v[152:155], v[230:233], v[16:19]
	v_mfma_f32_16x16x32_bf16 v[12:15], v[160:163], v[230:233], v[12:15]
	v_mfma_f32_16x16x32_bf16 v[56:59], v[164:167], v[180:183], v[56:59]
	v_mfma_f32_16x16x32_bf16 v[52:55], v[172:175], v[180:183], v[52:55]
	v_mfma_f32_16x16x32_bf16 v[40:43], v[164:167], v[188:191], v[40:43]
	v_mfma_f32_16x16x32_bf16 v[36:39], v[172:175], v[188:191], v[36:39]
	v_mfma_f32_16x16x32_bf16 v[24:27], v[164:167], v[204:207], v[24:27]
	v_mfma_f32_16x16x32_bf16 v[20:23], v[172:175], v[204:207], v[20:23]
	v_mfma_f32_16x16x32_bf16 v[8:11], v[164:167], v[212:215], v[8:11]
	v_mfma_f32_16x16x32_bf16 v[4:7], v[172:175], v[212:215], v[4:7]
	v_mfma_f32_16x16x32_bf16 v[56:59], v[168:171], v[184:187], v[56:59]
	v_mfma_f32_16x16x32_bf16 v[52:55], v[176:179], v[184:187], v[52:55]
	v_mfma_f32_16x16x32_bf16 v[40:43], v[168:171], v[192:195], v[40:43]
	v_mfma_f32_16x16x32_bf16 v[36:39], v[176:179], v[192:195], v[36:39]
	v_mfma_f32_16x16x32_bf16 v[24:27], v[168:171], v[208:211], v[24:27]
	v_mfma_f32_16x16x32_bf16 v[20:23], v[176:179], v[208:211], v[20:23]
	v_mfma_f32_16x16x32_bf16 v[8:11], v[168:171], v[230:233], v[8:11]
	v_mfma_f32_16x16x32_bf16 v[4:7], v[176:179], v[230:233], v[4:7]
	s_barrier
; #define PG8_STAGE(bufoff, gbase, voff) do { _Pragma("unroll") for (int _i = 0; _i < 2; ++_i) \
;         __builtin_amdgcn_global_load_lds((const unsigned*)((const char*)(gbase) + (voff)[_i]), (LAS unsigned*)(lds + (bufoff) + ldsw + _i * 8192), 16, 0, 0); } while (0)
; #define PG8_LDA(dst, b, h) do { _Pragma("unroll") for (int m = 0; m < 4; ++m) _Pragma("unroll") for (int k = 0; k < 2; ++k) dst[m][k] = *(const LAS bf16x8*)(lds + PG8_SA(b, h) + aoff + m * 2048 + k * 1024); } while (0)
; #define PG8_LDB(dst, b, h) do { _Pragma("unroll") for (int n = 0; n < 2; ++n) _Pragma("unroll") for (int k = 0; k < 2; ++k) dst[n][k] = *(const LAS bf16x8*)(lds + PG8_SB(b, h) + boff + n * 2048 + k * 1024); } while (0)
; #define PG8_MMA(ai, bj, At, Bt) do { __builtin_amdgcn_s_setprio(1); _Pragma("unroll") for (int m = 0; m < 4; ++m) _Pragma("unroll") for (int n = 0; n < 2; ++n) _Pragma("unroll") for (int k = 0; k < 2; ++k) \
;         acc[ai][bj][m][n] = __builtin_amdgcn_mfma_f32_16x16x32_bf16(Bt[n][k], At[m][k], acc[ai][bj][m][n], 0, 0, 0); __builtin_amdgcn_s_setprio(0); } while (0)
; #define PG8_WAIT_V(n) asm volatile("s_waitcnt vmcnt(" #n ")" ::: "memory")
; #define PG8_WAIT_L(n) asm volatile("s_waitcnt lgkmcnt(" #n ")" ::: "memory")
; #define PG8_BAR __builtin_amdgcn_s_barrier()
; #define PG8_SCHED __builtin_amdgcn_sched_barrier(0)
; template <class Epi, class Sched>
; DI void gemm_phase(LAS unsigned char* lds, const Sched& S, const Epi& E) {
;     ...
;             PG8_LDB(B0, 1, 0); PG8_LDB(B1, 1, 1); PG8_SCHED; PG8_LDA(At, 1, 0); PG8_STAGE(PG8_SA(0, 1), a2 + hstepA, voffA);
;             PG8_WAIT_V(8); PG8_WAIT_L(0); PG8_BAR; PG8_MMA(0, 0, At, B0); PG8_MMA(0, 1, At, B1); PG8_BAR; PG8_SCHED;
;             PG8_LDA(At, 1, 1); PG8_STAGE(PG8_SB(1, 0), b3, voffB); PG8_STAGE(PG8_SB(1, 1), b3 + hstepB, voffB); PG8_STAGE(PG8_SA(1, 0), a3, voffA);
;             PG8_WAIT_V(8); PG8_WAIT_L(0); PG8_BAR; PG8_MMA(1, 0, At, B0); PG8_MMA(1, 1, At, B1); PG8_BAR; PG8_SCHED;
;         }
;         if (wr == 0) PG8_BAR;
	s_add_i32 s66, 0, 0x18000
	s_add_i32 s67, 0, 0x1c000
	ds_read_b128 v[144:147], v216 offset:32768
	ds_read_b128 v[152:155], v216 offset:33792
	ds_read_b128 v[156:159], v216 offset:34816
	ds_read_b128 v[160:163], v216 offset:35840
	ds_read_b128 v[164:167], v216 offset:49152
	ds_read_b128 v[168:171], v216 offset:50176
	ds_read_b128 v[172:175], v216 offset:51200
	ds_read_b128 v[176:179], v216 offset:52224
	s_add_u32 s52, s52, 0x80000
	s_addc_u32 s53, s53, 0
	s_mov_b32 m0, s56
	ds_read_b128 v[180:183], v151 offset:32768
	ds_read_b128 v[184:187], v151 offset:33792
	ds_read_b128 v[188:191], v151 offset:34816
	ds_read_b128 v[192:195], v151 offset:35840
	ds_read_b128 v[204:207], v151 offset:36864
	ds_read_b128 v[208:211], v151 offset:37888
	ds_read_b128 v[212:215], v151 offset:38912
	global_load_lds_dwordx4 v132, s[52:53]
	s_mov_b32 m0, s57
	ds_read_b128 v[230:233], v151 offset:39936
	global_load_lds_dwordx4 v134, s[52:53]
	s_waitcnt vmcnt(8) lgkmcnt(0)
	s_barrier
	v_mfma_f32_16x16x32_bf16 v[128:131], v[144:147], v[180:183], v[128:131]
	v_mfma_f32_16x16x32_bf16 v[124:127], v[156:159], v[180:183], v[124:127]
	v_mfma_f32_16x16x32_bf16 v[112:115], v[144:147], v[188:191], v[112:115]
	v_mfma_f32_16x16x32_bf16 v[108:111], v[156:159], v[188:191], v[108:111]
	v_mfma_f32_16x16x32_bf16 v[96:99], v[144:147], v[204:207], v[96:99]
	v_mfma_f32_16x16x32_bf16 v[92:95], v[156:159], v[204:207], v[92:95]
	v_mfma_f32_16x16x32_bf16 v[80:83], v[144:147], v[212:215], v[80:83]
	v_mfma_f32_16x16x32_bf16 v[76:79], v[156:159], v[212:215], v[76:79]
	v_mfma_f32_16x16x32_bf16 v[128:131], v[152:155], v[184:187], v[128:131]
	v_mfma_f32_16x16x32_bf16 v[124:127], v[160:163], v[184:187], v[124:127]
	v_mfma_f32_16x16x32_bf16 v[112:115], v[152:155], v[192:195], v[112:115]
	v_mfma_f32_16x16x32_bf16 v[108:111], v[160:163], v[192:195], v[108:111]
	v_mfma_f32_16x16x32_bf16 v[96:99], v[152:155], v[208:211], v[96:99]
	v_mfma_f32_16x16x32_bf16 v[92:95], v[160:163], v[208:211], v[92:95]
	v_mfma_f32_16x16x32_bf16 v[80:83], v[152:155], v[230:233], v[80:83]
	v_mfma_f32_16x16x32_bf16 v[76:79], v[160:163], v[230:233], v[76:79]
	v_mfma_f32_16x16x32_bf16 v[120:123], v[164:167], v[180:183], v[120:123]
	v_mfma_f32_16x16x32_bf16 v[116:119], v[172:175], v[180:183], v[116:119]
	v_mfma_f32_16x16x32_bf16 v[104:107], v[164:167], v[188:191], v[104:107]
	v_mfma_f32_16x16x32_bf16 v[100:103], v[172:175], v[188:191], v[100:103]
	v_mfma_f32_16x16x32_bf16 v[88:91], v[164:167], v[204:207], v[88:91]
	v_mfma_f32_16x16x32_bf16 v[84:87], v[172:175], v[204:207], v[84:87]
	v_mfma_f32_16x16x32_bf16 v[72:75], v[164:167], v[212:215], v[72:75]
	v_mfma_f32_16x16x32_bf16 v[68:71], v[172:175], v[212:215], v[68:71]
	v_mfma_f32_16x16x32_bf16 v[120:123], v[168:171], v[184:187], v[120:123]
	v_mfma_f32_16x16x32_bf16 v[116:119], v[176:179], v[184:187], v[116:119]
	v_mfma_f32_16x16x32_bf16 v[104:107], v[168:171], v[192:195], v[104:107]
	v_mfma_f32_16x16x32_bf16 v[100:103], v[176:179], v[192:195], v[100:103]
	v_mfma_f32_16x16x32_bf16 v[88:91], v[168:171], v[208:211], v[88:91]
	v_mfma_f32_16x16x32_bf16 v[84:87], v[176:179], v[208:211], v[84:87]
	v_mfma_f32_16x16x32_bf16 v[72:75], v[168:171], v[230:233], v[72:75]
	v_mfma_f32_16x16x32_bf16 v[68:71], v[176:179], v[230:233], v[68:71]
	s_barrier
	s_add_i32 s52, s66, s27
	s_add_u32 s50, s50, 0x80
	s_addc_u32 s51, s51, 0
	s_mov_b32 m0, s52
	ds_read_b128 v[180:183], v151 offset:49152
	ds_read_b128 v[184:187], v151 offset:50176
	ds_read_b128 v[188:191], v151 offset:51200
	ds_read_b128 v[192:195], v151 offset:52224
	global_load_lds_dwordx4 v2, s[50:51]
	s_add_i32 m0, s52, 0x2000
	s_add_i32 s52, s67, s27
	global_load_lds_dwordx4 v136, s[50:51]
	s_add_u32 s50, s50, 0x80000
	s_addc_u32 s51, s51, 0
	s_mov_b32 m0, s52
	ds_read_b128 v[230:233], v151 offset:56320
	global_load_lds_dwordx4 v2, s[50:51]
	s_add_i32 m0, s52, 0x2000
	ds_read_b128 v[212:215], v151 offset:55296
	global_load_lds_dwordx4 v136, s[50:51]
	s_mov_b32 m0, s58
	ds_read_b128 v[208:211], v151 offset:54272
	global_load_lds_dwordx4 v132, s[86:87]
	s_mov_b32 m0, s59
	ds_read_b128 v[204:207], v151 offset:53248
	global_load_lds_dwordx4 v134, s[86:87]
	s_waitcnt vmcnt(8) lgkmcnt(0)
	s_barrier
	v_mfma_f32_16x16x32_bf16 v[64:67], v[144:147], v[180:183], v[64:67]
	v_mfma_f32_16x16x32_bf16 v[60:63], v[156:159], v[180:183], v[60:63]
	v_mfma_f32_16x16x32_bf16 v[48:51], v[144:147], v[188:191], v[48:51]
	v_mfma_f32_16x16x32_bf16 v[44:47], v[156:159], v[188:191], v[44:47]
	v_mfma_f32_16x16x32_bf16 v[32:35], v[144:147], v[204:207], v[32:35]
	v_mfma_f32_16x16x32_bf16 v[28:31], v[156:159], v[204:207], v[28:31]
	v_mfma_f32_16x16x32_bf16 v[16:19], v[144:147], v[212:215], v[16:19]
	v_mfma_f32_16x16x32_bf16 v[12:15], v[156:159], v[212:215], v[12:15]
	v_mfma_f32_16x16x32_bf16 v[64:67], v[152:155], v[184:187], v[64:67]
	v_mfma_f32_16x16x32_bf16 v[60:63], v[160:163], v[184:187], v[60:63]
	v_mfma_f32_16x16x32_bf16 v[48:51], v[152:155], v[192:195], v[48:51]
	v_mfma_f32_16x16x32_bf16 v[44:47], v[160:163], v[192:195], v[44:47]
	v_mfma_f32_16x16x32_bf16 v[32:35], v[152:155], v[208:211], v[32:35]
	v_mfma_f32_16x16x32_bf16 v[28:31], v[160:163], v[208:211], v[28:31]
	v_mfma_f32_16x16x32_bf16 v[16:19], v[152:155], v[230:233], v[16:19]
	v_mfma_f32_16x16x32_bf16 v[12:15], v[160:163], v[230:233], v[12:15]
	v_mfma_f32_16x16x32_bf16 v[56:59], v[164:167], v[180:183], v[56:59]
	v_mfma_f32_16x16x32_bf16 v[52:55], v[172:175], v[180:183], v[52:55]
	v_mfma_f32_16x16x32_bf16 v[40:43], v[164:167], v[188:191], v[40:43]
	v_mfma_f32_16x16x32_bf16 v[36:39], v[172:175], v[188:191], v[36:39]
	v_mfma_f32_16x16x32_bf16 v[24:27], v[164:167], v[204:207], v[24:27]
	v_mfma_f32_16x16x32_bf16 v[20:23], v[172:175], v[204:207], v[20:23]
	v_mfma_f32_16x16x32_bf16 v[8:11], v[164:167], v[212:215], v[8:11]
	v_mfma_f32_16x16x32_bf16 v[4:7], v[172:175], v[212:215], v[4:7]
	v_mfma_f32_16x16x32_bf16 v[56:59], v[168:171], v[184:187], v[56:59]
	v_mfma_f32_16x16x32_bf16 v[52:55], v[176:179], v[184:187], v[52:55]
	v_mfma_f32_16x16x32_bf16 v[40:43], v[168:171], v[192:195], v[40:43]
	v_mfma_f32_16x16x32_bf16 v[36:39], v[176:179], v[192:195], v[36:39]
	v_mfma_f32_16x16x32_bf16 v[24:27], v[168:171], v[208:211], v[24:27]
	v_mfma_f32_16x16x32_bf16 v[20:23], v[176:179], v[208:211], v[20:23]
	v_mfma_f32_16x16x32_bf16 v[8:11], v[168:171], v[230:233], v[8:11]
	v_mfma_f32_16x16x32_bf16 v[4:7], v[176:179], v[230:233], v[4:7]
	s_barrier
	s_add_i32 s65, s65, 2
	s_add_u32 s39, s39, 0x100
	s_addc_u32 s43, s43, 0
	s_add_u32 s48, s48, 0x100
	s_addc_u32 s49, s49, 0
	s_cmp_gt_u32 s65, 29
	s_cbranch_scc0 .LBB0_1390
	s_and_b64 vcc, exec, s[34:35]
	s_cbranch_vccz .LBB0_1393
	s_barrier

; #define PG8_STAGE(bufoff, gbase, voff) do { _Pragma("unroll") for (int _i = 0; _i < 2; ++_i) \
;         __builtin_amdgcn_global_load_lds((const unsigned*)((const char*)(gbase) + (voff)[_i]), (LAS unsigned*)(lds + (bufoff) + ldsw + _i * 8192), 16, 0, 0); } while (0)
; #define PG8_LDA(dst, b, h) do { _Pragma("unroll") for (int m = 0; m < 4; ++m) _Pragma("unroll") for (int k = 0; k < 2; ++k) dst[m][k] = *(const LAS bf16x8*)(lds + PG8_SA(b, h) + aoff + m * 2048 + k * 1024); } while (0)
; #define PG8_LDB(dst, b, h) do { _Pragma("unroll") for (int n = 0; n < 2; ++n) _Pragma("unroll") for (int k = 0; k < 2; ++k) dst[n][k] = *(const LAS bf16x8*)(lds + PG8_SB(b, h) + boff + n * 2048 + k * 1024); } while (0)
; #define PG8_MMA(ai, bj, At, Bt) do { __builtin_amdgcn_s_setprio(1); _Pragma("unroll") for (int m = 0; m < 4; ++m) _Pragma("unroll") for (int n = 0; n < 2; ++n) _Pragma("unroll") for (int k = 0; k < 2; ++k) \
;         acc[ai][bj][m][n] = __builtin_amdgcn_mfma_f32_16x16x32_bf16(Bt[n][k], At[m][k], acc[ai][bj][m][n], 0, 0, 0); __builtin_amdgcn_s_setprio(0); } while (0)
; #define PG8_WAIT_V(n) asm volatile("s_waitcnt vmcnt(" #n ")" ::: "memory")
; #define PG8_WAIT_L(n) asm volatile("s_waitcnt lgkmcnt(" #n ")" ::: "memory")
; #define PG8_BAR __builtin_amdgcn_s_barrier()
; template <class Epi, class Sched>
; DI void gemm_phase(LAS unsigned char* lds, const Sched& S, const Epi& E) {
;     ...
;         for (int t = 0; t < nt; t += 2) {
;             const bool last = (t == nt - 2);
;             const char* a1 = cA + (size_t)(t + 1) * kstep;
;             const char* a2 = last ? nA : cA + (size_t)(t + 2) * kstep; const char* b2 = last ? nB : cB + (size_t)(t + 2) * kstep;
;             const char* a3 = a2 + kstep; const char* b3 = b2 + kstep;
;             if constexpr (Epi::HOOK) { if (cur.ks < 0 && (t == 16 || t == 32)) E.hook(acc, cur, t >> 4, wr, wc, fr, fq); }
;             PG8_LDB(B0, 0, 0); PG8_LDB(B1, 0, 1); PG8_SCHED; PG8_LDA(At, 0, 0); PG8_STAGE(PG8_SA(1, 1), a1 + hstepA, voffA);
;             PG8_WAIT_V(8); PG8_WAIT_L(0); PG8_BAR; PG8_MMA(0, 0, At, B0); PG8_MMA(0, 1, At, B1); PG8_BAR; PG8_SCHED;
;             PG8_LDA(At, 0, 1); PG8_STAGE(PG8_SB(0, 0), b2, voffB); PG8_STAGE(PG8_SB(0, 1), b2 + hstepB, voffB); PG8_STAGE(PG8_SA(0, 0), a2, voffA);
;             PG8_WAIT_V(8); PG8_WAIT_L(0); PG8_BAR; PG8_MMA(1, 0, At, B0); PG8_MMA(1, 1, At, B1); PG8_BAR; PG8_SCHED;
.LBB0_1470:
	v_add_u32_e32 v214, 0x10000, v197
	s_add_i32 s82, s52, 2
	s_add_u32 s53, s42, 0xffe00080
	s_addc_u32 s54, s43, -1
	s_add_i32 s83, 0, 0x10000
	s_cmp_eq_u32 s79, s52
	s_cselect_b32 s55, s56, s54
	s_cselect_b32 s54, s57, s53
	s_cselect_b32 s53, s58, s81
	s_cselect_b32 s52, s59, s80
	s_add_i32 s85, 0, 0x14000
	ds_read_b128 v[84:87], v214
	ds_read_b128 v[88:91], v214 offset:1024
	ds_read_b128 v[104:107], v214 offset:2048
	ds_read_b128 v[112:115], v214 offset:3072
	ds_read_b128 v[124:127], v214 offset:16384
	ds_read_b128 v[136:139], v214 offset:17408
	ds_read_b128 v[148:151], v214 offset:18432
	ds_read_b128 v[160:163], v214 offset:19456
	s_add_i32 m0, s61, 0xc000
	ds_read_b128 v[164:167], v231
	ds_read_b128 v[168:171], v231 offset:1024
	ds_read_b128 v[172:175], v231 offset:2048
	ds_read_b128 v[176:179], v231 offset:3072
	ds_read_b128 v[180:183], v231 offset:4096
	ds_read_b128 v[184:187], v231 offset:5120
	ds_read_b128 v[188:191], v231 offset:6144
	global_load_lds_dwordx4 v212, s[42:43]
	s_add_i32 m0, s61, 0xe000
	ds_read_b128 v[192:195], v231 offset:7168
	global_load_lds_dwordx4 v210, s[42:43]
	s_waitcnt vmcnt(8) lgkmcnt(0)
	s_barrier
	v_mfma_f32_16x16x32_bf16 v[156:159], v[84:87], v[164:167], v[156:159]
	v_mfma_f32_16x16x32_bf16 v[152:155], v[104:107], v[164:167], v[152:155]
	v_mfma_f32_16x16x32_bf16 v[132:135], v[84:87], v[172:175], v[132:135]
	v_mfma_f32_16x16x32_bf16 v[128:131], v[104:107], v[172:175], v[128:131]
	v_mfma_f32_16x16x32_bf16 v[108:111], v[84:87], v[180:183], v[108:111]
	v_mfma_f32_16x16x32_bf16 v[100:103], v[104:107], v[180:183], v[100:103]
	v_mfma_f32_16x16x32_bf16 v[80:83], v[84:87], v[188:191], v[80:83]
	v_mfma_f32_16x16x32_bf16 v[76:79], v[104:107], v[188:191], v[76:79]
	v_mfma_f32_16x16x32_bf16 v[156:159], v[88:91], v[168:171], v[156:159]
	v_mfma_f32_16x16x32_bf16 v[152:155], v[112:115], v[168:171], v[152:155]
	v_mfma_f32_16x16x32_bf16 v[132:135], v[88:91], v[176:179], v[132:135]
	v_mfma_f32_16x16x32_bf16 v[128:131], v[112:115], v[176:179], v[128:131]
	v_mfma_f32_16x16x32_bf16 v[108:111], v[88:91], v[184:187], v[108:111]
	v_mfma_f32_16x16x32_bf16 v[100:103], v[112:115], v[184:187], v[100:103]
	v_mfma_f32_16x16x32_bf16 v[80:83], v[88:91], v[192:195], v[80:83]
	v_mfma_f32_16x16x32_bf16 v[76:79], v[112:115], v[192:195], v[76:79]
	v_mfma_f32_16x16x32_bf16 v[144:147], v[124:127], v[164:167], v[144:147]
	v_mfma_f32_16x16x32_bf16 v[140:143], v[148:151], v[164:167], v[140:143]
	v_mfma_f32_16x16x32_bf16 v[120:123], v[124:127], v[172:175], v[120:123]
	v_mfma_f32_16x16x32_bf16 v[116:119], v[148:151], v[172:175], v[116:119]
	v_mfma_f32_16x16x32_bf16 v[96:99], v[124:127], v[180:183], v[96:99]
	v_mfma_f32_16x16x32_bf16 v[92:95], v[148:151], v[180:183], v[92:95]
	v_mfma_f32_16x16x32_bf16 v[72:75], v[124:127], v[188:191], v[72:75]
	v_mfma_f32_16x16x32_bf16 v[68:71], v[148:151], v[188:191], v[68:71]
	v_mfma_f32_16x16x32_bf16 v[144:147], v[136:139], v[168:171], v[144:147]
	v_mfma_f32_16x16x32_bf16 v[140:143], v[160:163], v[168:171], v[140:143]
	v_mfma_f32_16x16x32_bf16 v[120:123], v[136:139], v[176:179], v[120:123]
	v_mfma_f32_16x16x32_bf16 v[116:119], v[160:163], v[176:179], v[116:119]
	v_mfma_f32_16x16x32_bf16 v[96:99], v[136:139], v[184:187], v[96:99]
	v_mfma_f32_16x16x32_bf16 v[92:95], v[160:163], v[184:187], v[92:95]
	v_mfma_f32_16x16x32_bf16 v[72:75], v[136:139], v[192:195], v[72:75]
	v_mfma_f32_16x16x32_bf16 v[68:71], v[160:163], v[192:195], v[68:71]
	s_barrier
	s_add_i32 s83, s83, s60
	s_mov_b32 m0, s83
	ds_read_b128 v[164:167], v231 offset:16384
	ds_read_b128 v[168:171], v231 offset:17408
	ds_read_b128 v[172:175], v231 offset:18432
	ds_read_b128 v[176:179], v231 offset:19456
	global_load_lds_dwordx4 v2, s[52:53]
	s_add_i32 m0, s83, 0x2000
	s_add_u32 s86, s52, 0x200000
	s_addc_u32 s87, s53, 0
	s_add_i32 s83, s85, s60
	global_load_lds_dwordx4 v208, s[52:53]
	s_mov_b32 m0, s83
	ds_read_b128 v[192:195], v231 offset:23552
	global_load_lds_dwordx4 v2, s[86:87]
	s_add_i32 m0, s83, 0x2000
	ds_read_b128 v[188:191], v231 offset:22528
	global_load_lds_dwordx4 v208, s[86:87]
	s_add_u32 s98, s54, 0x80
	s_addc_u32 s99, s55, 0
	s_mov_b32 m0, s61
	ds_read_b128 v[184:187], v231 offset:21504
	global_load_lds_dwordx4 v204, s[54:55]
	s_mov_b32 m0, s62
	ds_read_b128 v[180:183], v231 offset:20480
	global_load_lds_dwordx4 v206, s[54:55]
	s_waitcnt vmcnt(8) lgkmcnt(0)
	s_barrier
	v_mfma_f32_16x16x32_bf16 v[64:67], v[84:87], v[164:167], v[64:67]
	v_mfma_f32_16x16x32_bf16 v[60:63], v[104:107], v[164:167], v[60:63]
	v_mfma_f32_16x16x32_bf16 v[48:51], v[84:87], v[172:175], v[48:51]
	v_mfma_f32_16x16x32_bf16 v[44:47], v[104:107], v[172:175], v[44:47]
	v_mfma_f32_16x16x32_bf16 v[32:35], v[84:87], v[180:183], v[32:35]
	v_mfma_f32_16x16x32_bf16 v[28:31], v[104:107], v[180:183], v[28:31]
	v_mfma_f32_16x16x32_bf16 v[16:19], v[84:87], v[188:191], v[16:19]
	v_mfma_f32_16x16x32_bf16 v[12:15], v[104:107], v[188:191], v[12:15]
	v_mfma_f32_16x16x32_bf16 v[64:67], v[88:91], v[168:171], v[64:67]
	v_mfma_f32_16x16x32_bf16 v[60:63], v[112:115], v[168:171], v[60:63]
	v_mfma_f32_16x16x32_bf16 v[48:51], v[88:91], v[176:179], v[48:51]
	v_mfma_f32_16x16x32_bf16 v[44:47], v[112:115], v[176:179], v[44:47]
	v_mfma_f32_16x16x32_bf16 v[32:35], v[88:91], v[184:187], v[32:35]
	v_mfma_f32_16x16x32_bf16 v[28:31], v[112:115], v[184:187], v[28:31]
	v_mfma_f32_16x16x32_bf16 v[16:19], v[88:91], v[192:195], v[16:19]
	v_mfma_f32_16x16x32_bf16 v[12:15], v[112:115], v[192:195], v[12:15]
	v_mfma_f32_16x16x32_bf16 v[56:59], v[124:127], v[164:167], v[56:59]
	v_mfma_f32_16x16x32_bf16 v[52:55], v[148:151], v[164:167], v[52:55]
	v_mfma_f32_16x16x32_bf16 v[40:43], v[124:127], v[172:175], v[40:43]
	v_mfma_f32_16x16x32_bf16 v[36:39], v[148:151], v[172:175], v[36:39]
	v_mfma_f32_16x16x32_bf16 v[24:27], v[124:127], v[180:183], v[24:27]
	v_mfma_f32_16x16x32_bf16 v[20:23], v[148:151], v[180:183], v[20:23]
	v_mfma_f32_16x16x32_bf16 v[8:11], v[124:127], v[188:191], v[8:11]
	v_mfma_f32_16x16x32_bf16 v[4:7], v[148:151], v[188:191], v[4:7]
	v_mfma_f32_16x16x32_bf16 v[56:59], v[136:139], v[168:171], v[56:59]
	v_mfma_f32_16x16x32_bf16 v[52:55], v[160:163], v[168:171], v[52:55]
	v_mfma_f32_16x16x32_bf16 v[40:43], v[136:139], v[176:179], v[40:43]
	v_mfma_f32_16x16x32_bf16 v[36:39], v[160:163], v[176:179], v[36:39]
	v_mfma_f32_16x16x32_bf16 v[24:27], v[136:139], v[184:187], v[24:27]
	v_mfma_f32_16x16x32_bf16 v[20:23], v[160:163], v[184:187], v[20:23]
	v_mfma_f32_16x16x32_bf16 v[8:11], v[136:139], v[192:195], v[8:11]
	v_mfma_f32_16x16x32_bf16 v[4:7], v[160:163], v[192:195], v[4:7]
	s_barrier
; #define PG8_STAGE(bufoff, gbase, voff) do { _Pragma("unroll") for (int _i = 0; _i < 2; ++_i) \
;         __builtin_amdgcn_global_load_lds((const unsigned*)((const char*)(gbase) + (voff)[_i]), (LAS unsigned*)(lds + (bufoff) + ldsw + _i * 8192), 16, 0, 0); } while (0)
; #define PG8_LDA(dst, b, h) do { _Pragma("unroll") for (int m = 0; m < 4; ++m) _Pragma("unroll") for (int k = 0; k < 2; ++k) dst[m][k] = *(const LAS bf16x8*)(lds + PG8_SA(b, h) + aoff + m * 2048 + k * 1024); } while (0)
; #define PG8_LDB(dst, b, h) do { _Pragma("unroll") for (int n = 0; n < 2; ++n) _Pragma("unroll") for (int k = 0; k < 2; ++k) dst[n][k] = *(const LAS bf16x8*)(lds + PG8_SB(b, h) + boff + n * 2048 + k * 1024); } while (0)
; #define PG8_MMA(ai, bj, At, Bt) do { __builtin_amdgcn_s_setprio(1); _Pragma("unroll") for (int m = 0; m < 4; ++m) _Pragma("unroll") for (int n = 0; n < 2; ++n) _Pragma("unroll") for (int k = 0; k < 2; ++k) \
;         acc[ai][bj][m][n] = __builtin_amdgcn_mfma_f32_16x16x32_bf16(Bt[n][k], At[m][k], acc[ai][bj][m][n], 0, 0, 0); __builtin_amdgcn_s_setprio(0); } while (0)
; #define PG8_WAIT_V(n) asm volatile("s_waitcnt vmcnt(" #n ")" ::: "memory")
; #define PG8_WAIT_L(n) asm volatile("s_waitcnt lgkmcnt(" #n ")" ::: "memory")
; #define PG8_BAR __builtin_amdgcn_s_barrier()
; #define PG8_SCHED __builtin_amdgcn_sched_barrier(0)
; template <class Epi, class Sched>
; DI void gemm_phase(LAS unsigned char* lds, const Sched& S, const Epi& E) {
;     ...
;             PG8_LDB(B0, 1, 0); PG8_LDB(B1, 1, 1); PG8_SCHED; PG8_LDA(At, 1, 0); PG8_STAGE(PG8_SA(0, 1), a2 + hstepA, voffA);
;             PG8_WAIT_V(8); PG8_WAIT_L(0); PG8_BAR; PG8_MMA(0, 0, At, B0); PG8_MMA(0, 1, At, B1); PG8_BAR; PG8_SCHED;
;             PG8_LDA(At, 1, 1); PG8_STAGE(PG8_SB(1, 0), b3, voffB); PG8_STAGE(PG8_SB(1, 1), b3 + hstepB, voffB); PG8_STAGE(PG8_SA(1, 0), a3, voffA);
;             PG8_WAIT_V(8); PG8_WAIT_L(0); PG8_BAR; PG8_MMA(1, 0, At, B0); PG8_MMA(1, 1, At, B1); PG8_BAR; PG8_SCHED;
;         }
;         if (wr == 0) PG8_BAR;
	s_add_i32 s83, 0, 0x18000
	s_add_i32 s85, 0, 0x1c000
	ds_read_b128 v[84:87], v214 offset:32768
	ds_read_b128 v[88:91], v214 offset:33792
	ds_read_b128 v[104:107], v214 offset:34816
	ds_read_b128 v[112:115], v214 offset:35840
	ds_read_b128 v[124:127], v214 offset:49152
	ds_read_b128 v[136:139], v214 offset:50176
	ds_read_b128 v[148:151], v214 offset:51200
	ds_read_b128 v[160:163], v214 offset:52224
	s_add_u32 s54, s54, 0x200000
	s_addc_u32 s55, s55, 0
	s_mov_b32 m0, s63
	ds_read_b128 v[164:167], v231 offset:32768
	ds_read_b128 v[168:171], v231 offset:33792
	ds_read_b128 v[172:175], v231 offset:34816
	ds_read_b128 v[176:179], v231 offset:35840
	ds_read_b128 v[180:183], v231 offset:36864
	ds_read_b128 v[184:187], v231 offset:37888
	ds_read_b128 v[188:191], v231 offset:38912
	global_load_lds_dwordx4 v204, s[54:55]
	s_mov_b32 m0, s64
	ds_read_b128 v[192:195], v231 offset:39936
	global_load_lds_dwordx4 v206, s[54:55]
	s_waitcnt vmcnt(8) lgkmcnt(0)
	s_barrier
	v_mfma_f32_16x16x32_bf16 v[156:159], v[84:87], v[164:167], v[156:159]
	v_mfma_f32_16x16x32_bf16 v[152:155], v[104:107], v[164:167], v[152:155]
	v_mfma_f32_16x16x32_bf16 v[132:135], v[84:87], v[172:175], v[132:135]
	v_mfma_f32_16x16x32_bf16 v[128:131], v[104:107], v[172:175], v[128:131]
	v_mfma_f32_16x16x32_bf16 v[108:111], v[84:87], v[180:183], v[108:111]
	v_mfma_f32_16x16x32_bf16 v[100:103], v[104:107], v[180:183], v[100:103]
	v_mfma_f32_16x16x32_bf16 v[80:83], v[84:87], v[188:191], v[80:83]
	v_mfma_f32_16x16x32_bf16 v[76:79], v[104:107], v[188:191], v[76:79]
	v_mfma_f32_16x16x32_bf16 v[156:159], v[88:91], v[168:171], v[156:159]
	v_mfma_f32_16x16x32_bf16 v[152:155], v[112:115], v[168:171], v[152:155]
	v_mfma_f32_16x16x32_bf16 v[132:135], v[88:91], v[176:179], v[132:135]
	v_mfma_f32_16x16x32_bf16 v[128:131], v[112:115], v[176:179], v[128:131]
	v_mfma_f32_16x16x32_bf16 v[108:111], v[88:91], v[184:187], v[108:111]
	v_mfma_f32_16x16x32_bf16 v[100:103], v[112:115], v[184:187], v[100:103]
	v_mfma_f32_16x16x32_bf16 v[80:83], v[88:91], v[192:195], v[80:83]
	v_mfma_f32_16x16x32_bf16 v[76:79], v[112:115], v[192:195], v[76:79]
	v_mfma_f32_16x16x32_bf16 v[144:147], v[124:127], v[164:167], v[144:147]
	v_mfma_f32_16x16x32_bf16 v[140:143], v[148:151], v[164:167], v[140:143]
	v_mfma_f32_16x16x32_bf16 v[120:123], v[124:127], v[172:175], v[120:123]
	v_mfma_f32_16x16x32_bf16 v[116:119], v[148:151], v[172:175], v[116:119]
	v_mfma_f32_16x16x32_bf16 v[96:99], v[124:127], v[180:183], v[96:99]
	v_mfma_f32_16x16x32_bf16 v[92:95], v[148:151], v[180:183], v[92:95]
	v_mfma_f32_16x16x32_bf16 v[72:75], v[124:127], v[188:191], v[72:75]
	v_mfma_f32_16x16x32_bf16 v[68:71], v[148:151], v[188:191], v[68:71]
	v_mfma_f32_16x16x32_bf16 v[144:147], v[136:139], v[168:171], v[144:147]
	v_mfma_f32_16x16x32_bf16 v[140:143], v[160:163], v[168:171], v[140:143]
	v_mfma_f32_16x16x32_bf16 v[120:123], v[136:139], v[176:179], v[120:123]
	v_mfma_f32_16x16x32_bf16 v[116:119], v[160:163], v[176:179], v[116:119]
	v_mfma_f32_16x16x32_bf16 v[96:99], v[136:139], v[184:187], v[96:99]
	v_mfma_f32_16x16x32_bf16 v[92:95], v[160:163], v[184:187], v[92:95]
	v_mfma_f32_16x16x32_bf16 v[72:75], v[136:139], v[192:195], v[72:75]
	v_mfma_f32_16x16x32_bf16 v[68:71], v[160:163], v[192:195], v[68:71]
	s_barrier
	s_add_i32 s54, s83, s60
	s_add_u32 s52, s52, 0x80
	s_addc_u32 s53, s53, 0
	s_mov_b32 m0, s54
	ds_read_b128 v[164:167], v231 offset:49152
	ds_read_b128 v[168:171], v231 offset:50176
	ds_read_b128 v[172:175], v231 offset:51200
	ds_read_b128 v[176:179], v231 offset:52224
	global_load_lds_dwordx4 v2, s[52:53]
	s_add_i32 m0, s54, 0x2000
	s_add_i32 s54, s85, s60
	global_load_lds_dwordx4 v208, s[52:53]
	s_add_u32 s52, s52, 0x200000
	s_addc_u32 s53, s53, 0
	s_mov_b32 m0, s54
	ds_read_b128 v[192:195], v231 offset:56320
	global_load_lds_dwordx4 v2, s[52:53]
	s_add_i32 m0, s54, 0x2000
	ds_read_b128 v[188:191], v231 offset:55296
	global_load_lds_dwordx4 v208, s[52:53]
	s_mov_b32 m0, s71
	ds_read_b128 v[184:187], v231 offset:54272
	global_load_lds_dwordx4 v204, s[98:99]
	s_mov_b32 m0, s72
	ds_read_b128 v[180:183], v231 offset:53248
	global_load_lds_dwordx4 v206, s[98:99]
	s_waitcnt vmcnt(8) lgkmcnt(0)
	s_barrier
	v_mfma_f32_16x16x32_bf16 v[64:67], v[84:87], v[164:167], v[64:67]
	v_mfma_f32_16x16x32_bf16 v[60:63], v[104:107], v[164:167], v[60:63]
	v_mfma_f32_16x16x32_bf16 v[48:51], v[84:87], v[172:175], v[48:51]
	v_mfma_f32_16x16x32_bf16 v[44:47], v[104:107], v[172:175], v[44:47]
	v_mfma_f32_16x16x32_bf16 v[32:35], v[84:87], v[180:183], v[32:35]
	v_mfma_f32_16x16x32_bf16 v[28:31], v[104:107], v[180:183], v[28:31]
	v_mfma_f32_16x16x32_bf16 v[16:19], v[84:87], v[188:191], v[16:19]
	v_mfma_f32_16x16x32_bf16 v[12:15], v[104:107], v[188:191], v[12:15]
	v_mfma_f32_16x16x32_bf16 v[64:67], v[88:91], v[168:171], v[64:67]
	v_mfma_f32_16x16x32_bf16 v[60:63], v[112:115], v[168:171], v[60:63]
	v_mfma_f32_16x16x32_bf16 v[48:51], v[88:91], v[176:179], v[48:51]
	v_mfma_f32_16x16x32_bf16 v[44:47], v[112:115], v[176:179], v[44:47]
	v_mfma_f32_16x16x32_bf16 v[32:35], v[88:91], v[184:187], v[32:35]
	v_mfma_f32_16x16x32_bf16 v[28:31], v[112:115], v[184:187], v[28:31]
	v_mfma_f32_16x16x32_bf16 v[16:19], v[88:91], v[192:195], v[16:19]
	v_mfma_f32_16x16x32_bf16 v[12:15], v[112:115], v[192:195], v[12:15]
	v_mfma_f32_16x16x32_bf16 v[56:59], v[124:127], v[164:167], v[56:59]
	v_mfma_f32_16x16x32_bf16 v[52:55], v[148:151], v[164:167], v[52:55]
	v_mfma_f32_16x16x32_bf16 v[40:43], v[124:127], v[172:175], v[40:43]
	v_mfma_f32_16x16x32_bf16 v[36:39], v[148:151], v[172:175], v[36:39]
	v_mfma_f32_16x16x32_bf16 v[24:27], v[124:127], v[180:183], v[24:27]
	v_mfma_f32_16x16x32_bf16 v[20:23], v[148:151], v[180:183], v[20:23]
	v_mfma_f32_16x16x32_bf16 v[8:11], v[124:127], v[188:191], v[8:11]
	v_mfma_f32_16x16x32_bf16 v[4:7], v[148:151], v[188:191], v[4:7]
	v_mfma_f32_16x16x32_bf16 v[56:59], v[136:139], v[168:171], v[56:59]
	v_mfma_f32_16x16x32_bf16 v[52:55], v[160:163], v[168:171], v[52:55]
	v_mfma_f32_16x16x32_bf16 v[40:43], v[136:139], v[176:179], v[40:43]
	v_mfma_f32_16x16x32_bf16 v[36:39], v[160:163], v[176:179], v[36:39]
	v_mfma_f32_16x16x32_bf16 v[24:27], v[136:139], v[184:187], v[24:27]
	v_mfma_f32_16x16x32_bf16 v[20:23], v[160:163], v[184:187], v[20:23]
	v_mfma_f32_16x16x32_bf16 v[8:11], v[136:139], v[192:195], v[8:11]
	v_mfma_f32_16x16x32_bf16 v[4:7], v[160:163], v[192:195], v[4:7]
	s_barrier
	s_add_u32 s80, s80, 0x100
	s_addc_u32 s81, s81, 0
	s_add_u32 s42, s42, 0x100
	s_addc_u32 s43, s43, 0
	s_cmp_ge_i32 s82, s75
	s_mov_b32 s52, s82
	s_cbranch_scc0 .LBB0_1470
	s_and_b64 vcc, exec, s[38:39]
	s_cbranch_vccz .LBB0_1473
	s_barrier
